# v032 + GEMM K-loops: saddr-form LDS-DMA requests (8 VALU adds/iteration removed) + loop-edge rotation (pointer increments and next-tile selects moved behind the first fragment reads / requests)
# speedup vs baseline: 1.0047x; 1.0002x over previous
; #define PG8_STAGE(bufoff, gbase, voff) do { _Pragma("unroll") for (int _i = 0; _i < 2; ++_i) \
;         __builtin_amdgcn_global_load_lds((const unsigned*)((const char*)(gbase) + (voff)[_i]), (PG8_LAS unsigned*)(lds + (bufoff) + ldsw + _i * 8192), 16, 0, 0); } while (0)
; #define PG8_LDA(dst, b, h) do { _Pragma("unroll") for (int m = 0; m < 4; ++m) _Pragma("unroll") for (int k = 0; k < 2; ++k) dst[m][k] = *(const PG8_LAS bf16x8*)(lds + PG8_SA(b, h) + aoff + m * 2048 + k * 1024); } while (0)
; #define PG8_LDB(dst, b, h) do { _Pragma("unroll") for (int n = 0; n < 2; ++n) _Pragma("unroll") for (int k = 0; k < 2; ++k) dst[n][k] = *(const PG8_LAS bf16x8*)(lds + PG8_SB(b, h) + boff + n * 2048 + k * 1024); } while (0)
; #define PG8_WAIT_V(n) asm volatile("s_waitcnt vmcnt(" #n ")" ::: "memory")
; #define PG8_BAR __builtin_amdgcn_s_barrier()
; template <class Epi, class Sched, bool ALIGN_EPI = false, bool SP2 = false, bool GEN = false>
; __device__ __forceinline__ void gemm_phase(PG8_LAS unsigned char* lds, const Gemm g, const Sched& S, const Epi& E, int wave_) {
;     ...
;     Unit cur, nxt; int ui = 0;
;     if (!S.next(0, cur)) return;
;     f32x4 acc[2][2][4][2];
; #pragma unroll
;     for (int a = 0; a < 2; ++a)
; #pragma unroll
;         for (int b = 0; b < 2; ++b)
; #pragma unroll
;             for (int m = 0; m < 4; ++m)
; #pragma unroll
;                 for (int n = 0; n < 2; ++n) acc[a][b][m][n] = (f32x4){0.f, 0.f, 0.f, 0.f};
;     ...
;     for (;;) {
;         const bool has_next = S.next(ui + 1, nxt);
;         const char* nA = has_next ? (const char*)g.A + (size_t)nxt.pm * tstepA + (GEN ? S.acol(nxt) * 2 : 0) : cA; const char* nB = has_next ? (const char*)g.Bt + (size_t)nxt.pn * tstepB : cB;
;         for (int t = 0; t < nt; t += 2) {
;             const bool last = (t == nt - 2);
;             const char* a1 = cA + (size_t)(t + 1) * kstep;
;             const char* a2 = last ? nA : cA + (size_t)(t + 2) * kstep; const char* b2 = last ? nB : cB + (size_t)(t + 2) * kstep;
;             const char* a3 = a2 + kstep; const char* b3 = b2 + kstep;
;             if (last && has_next) S.a_ready(nxt);
;             if constexpr (SP2) {
;             PG8_LDB(B0, 0, 0); PG8_LDB(B1, 0, 1); PG8_SCHED; PG8_LDA(At, 0, 0); PG8_STAGE(PG8_SA(1, 1), a1 + hstepA, voffA);
;             PG8_WAIT_V(8); PG8_WAIT_L(0); PG8_BAR; PG8_MMA(0, 0, At, B0); PG8_MMA(0, 1, At, B1); PG8_BAR; PG8_SCHED;
.LBB0_109:
	s_ashr_i32 s53, s52, 31
	s_lshl_b64 s[36:37], s[52:53], 21
	s_add_u32 s54, s34, s36
	s_addc_u32 s55, s35, s37
	s_and_b64 s[36:37], s[40:41], exec
	s_cselect_b32 s36, s55, s15
	s_cselect_b32 s37, s54, s14
	s_ashr_i32 s51, s50, 31
	s_lshl_b64 s[56:57], s[50:51], 21
	s_add_u32 s56, s42, s56
	s_addc_u32 s57, s43, s57
	s_and_b64 s[58:59], s[40:41], exec
	s_cselect_b32 s51, s57, s29
	s_cselect_b32 s53, s56, s28
	s_add_u32 s65, s28, 0x100
	s_addc_u32 s66, s29, 0
	s_add_u32 s58, s14, 0x100080
	v_mov_b32_e32 v2, 0
	s_addc_u32 s59, s15, 0
	s_mov_b32 s67, -2
	v_mov_b32_e32 v3, v2
	v_mov_b32_e32 v4, v2
	v_mov_b32_e32 v5, v2
	v_mov_b32_e32 v6, v2
	v_mov_b32_e32 v7, v2
	v_mov_b32_e32 v8, v2
	v_mov_b32_e32 v9, v2
	v_mov_b32_e32 v10, v2
	v_mov_b32_e32 v11, v2
	v_mov_b32_e32 v12, v2
	v_mov_b32_e32 v13, v2
	s_waitcnt vmcnt(0)
	v_mov_b32_e32 v18, v2
	v_mov_b32_e32 v19, v2
	v_mov_b32_e32 v20, v2
	v_mov_b32_e32 v21, v2
	v_mov_b32_e32 v26, v2
	v_mov_b32_e32 v27, v2
	v_mov_b32_e32 v28, v2
	v_mov_b32_e32 v29, v2
	v_mov_b32_e32 v34, v2
	v_mov_b32_e32 v35, v2
	v_mov_b32_e32 v36, v2
	v_mov_b32_e32 v37, v2
	v_mov_b32_e32 v42, v2
	v_mov_b32_e32 v43, v2
	v_mov_b32_e32 v44, v2
	v_mov_b32_e32 v45, v2
	v_mov_b32_e32 v50, v2
	v_mov_b32_e32 v51, v2
	v_mov_b32_e32 v52, v2
	v_mov_b32_e32 v53, v2
	v_mov_b32_e32 v14, v2
	v_mov_b32_e32 v15, v2
	v_mov_b32_e32 v16, v2
	v_mov_b32_e32 v17, v2
	v_mov_b32_e32 v22, v2
	v_mov_b32_e32 v23, v2
	v_mov_b32_e32 v24, v2
	v_mov_b32_e32 v25, v2
	v_mov_b32_e32 v30, v2
	v_mov_b32_e32 v31, v2
	v_mov_b32_e32 v32, v2
	v_mov_b32_e32 v33, v2
	v_mov_b32_e32 v38, v2
	v_mov_b32_e32 v39, v2
	v_mov_b32_e32 v40, v2
	v_mov_b32_e32 v41, v2
	v_mov_b32_e32 v46, v2
	v_mov_b32_e32 v47, v2
	v_mov_b32_e32 v48, v2
	v_mov_b32_e32 v49, v2
	v_mov_b32_e32 v54, v2
	v_mov_b32_e32 v55, v2
	v_mov_b32_e32 v56, v2
	v_mov_b32_e32 v57, v2
	v_mov_b32_e32 v58, v2
	v_mov_b32_e32 v59, v2
	v_mov_b32_e32 v60, v2
	v_mov_b32_e32 v61, v2
	v_mov_b32_e32 v62, v2
	v_mov_b32_e32 v63, v2
	v_mov_b32_e32 v64, v2
	v_mov_b32_e32 v65, v2
	v_mov_b32_e32 v66, v2
	v_mov_b32_e32 v67, v2
	v_mov_b32_e32 v68, v2
	v_mov_b32_e32 v69, v2
	v_mov_b32_e32 v70, v2
	v_mov_b32_e32 v71, v2
	v_mov_b32_e32 v72, v2
	v_mov_b32_e32 v73, v2
	v_mov_b32_e32 v74, v2
	v_mov_b32_e32 v75, v2
	v_mov_b32_e32 v76, v2
	v_mov_b32_e32 v77, v2
	v_mov_b32_e32 v82, v2
	v_mov_b32_e32 v83, v2
	v_mov_b32_e32 v84, v2
	v_mov_b32_e32 v85, v2
	v_mov_b32_e32 v90, v2
	v_mov_b32_e32 v91, v2
	v_mov_b32_e32 v92, v2
	v_mov_b32_e32 v93, v2
	v_mov_b32_e32 v98, v2
	v_mov_b32_e32 v99, v2
	v_mov_b32_e32 v100, v2
	v_mov_b32_e32 v101, v2
	v_mov_b32_e32 v106, v2
	v_mov_b32_e32 v107, v2
	v_mov_b32_e32 v108, v2
	v_mov_b32_e32 v109, v2
	v_mov_b32_e32 v114, v2
	v_mov_b32_e32 v115, v2
	v_mov_b32_e32 v116, v2
	v_mov_b32_e32 v117, v2
	v_mov_b32_e32 v78, v2
	v_mov_b32_e32 v79, v2
	v_mov_b32_e32 v80, v2
	v_mov_b32_e32 v81, v2
	v_mov_b32_e32 v86, v2
	v_mov_b32_e32 v87, v2
	v_mov_b32_e32 v88, v2
	v_mov_b32_e32 v89, v2
	v_mov_b32_e32 v94, v2
	v_mov_b32_e32 v95, v2
	v_mov_b32_e32 v96, v2
	v_mov_b32_e32 v97, v2
	v_mov_b32_e32 v102, v2
	v_mov_b32_e32 v103, v2
	v_mov_b32_e32 v104, v2
	v_mov_b32_e32 v105, v2
	v_mov_b32_e32 v110, v2
	v_mov_b32_e32 v111, v2
	v_mov_b32_e32 v112, v2
	v_mov_b32_e32 v113, v2
	v_mov_b32_e32 v118, v2
	v_mov_b32_e32 v119, v2
	v_mov_b32_e32 v120, v2
	v_mov_b32_e32 v121, v2
	v_mov_b32_e32 v122, v2
	v_mov_b32_e32 v123, v2
	v_mov_b32_e32 v124, v2
	v_mov_b32_e32 v125, v2
	v_mov_b32_e32 v126, v2
	v_mov_b32_e32 v127, v2
	v_mov_b32_e32 v128, v2
	v_mov_b32_e32 v129, v2
	s_add_i32 s67, s67, -2
	s_sub_u32 s65, s65, 0x100
	s_subb_u32 s66, s66, 0
	s_sub_u32 s58, s58, 0x100
	s_subb_u32 s59, s59, 0
.LBB0_110:
	v_add_u32_e32 v156, 0x10000, v145
	v_add_u32_e32 v172, 0x14000, v145
	ds_read_b128 v[140:143], v156
	ds_read_b128 v[148:151], v156 offset:1024
	ds_read_b128 v[152:155], v156 offset:2048
	ds_read_b128 v[156:159], v156 offset:3072
	ds_read_b128 v[160:163], v172
	ds_read_b128 v[164:167], v172 offset:1024
	ds_read_b128 v[168:171], v172 offset:2048
	ds_read_b128 v[172:175], v172 offset:3072
	s_add_i32 m0, s19, 0xc000
	ds_read_b128 v[176:179], v147
	ds_read_b128 v[180:183], v147 offset:1024
	ds_read_b128 v[184:187], v147 offset:2048
	ds_read_b128 v[188:191], v147 offset:3072
	ds_read_b128 v[192:195], v147 offset:4096
	ds_read_b128 v[196:199], v147 offset:5120
	ds_read_b128 v[200:203], v147 offset:6144
	ds_read_b128 v[204:207], v147 offset:7168
	s_add_i32 s67, s67, 2
	s_add_u32 s65, s65, 0x100
	s_addc_u32 s66, s66, 0
	s_add_u32 s58, s58, 0x100
	s_addc_u32 s59, s59, 0
	global_load_lds_dwordx4 v138, s[58:59]
	s_add_i32 m0, s19, 0xe000
	s_nop 0
	global_load_lds_dwordx4 v136, s[58:59]
	s_add_i32 s24, 0, 0x10000
	s_add_i32 s74, 0, 0x14000
	s_add_u32 s14, s58, 0xfff00080
	s_addc_u32 s15, s59, -1
	s_cmp_eq_u32 s67, 60
	s_cselect_b32 s29, s36, s15
	s_cselect_b32 s28, s37, s14
	s_cselect_b32 s15, s51, s66
	s_cselect_b32 s14, s53, s65
	s_waitcnt vmcnt(8)
	s_waitcnt lgkmcnt(0)
	s_barrier
; #define PG8_STAGE(bufoff, gbase, voff) do { _Pragma("unroll") for (int _i = 0; _i < 2; ++_i) \
;         __builtin_amdgcn_global_load_lds((const unsigned*)((const char*)(gbase) + (voff)[_i]), (PG8_LAS unsigned*)(lds + (bufoff) + ldsw + _i * 8192), 16, 0, 0); } while (0)
; #define PG8_LDA(dst, b, h) do { _Pragma("unroll") for (int m = 0; m < 4; ++m) _Pragma("unroll") for (int k = 0; k < 2; ++k) dst[m][k] = *(const PG8_LAS bf16x8*)(lds + PG8_SA(b, h) + aoff + m * 2048 + k * 1024); } while (0)
; #define PG8_LDB(dst, b, h) do { _Pragma("unroll") for (int n = 0; n < 2; ++n) _Pragma("unroll") for (int k = 0; k < 2; ++k) dst[n][k] = *(const PG8_LAS bf16x8*)(lds + PG8_SB(b, h) + boff + n * 2048 + k * 1024); } while (0)
; #define PG8_MMA(ai, bj, At, Bt) do { __builtin_amdgcn_s_setprio(1); _Pragma("unroll") for (int m = 0; m < 4; ++m) _Pragma("unroll") for (int n = 0; n < 2; ++n) _Pragma("unroll") for (int k = 0; k < 2; ++k) \
;         acc[ai][bj][m][n] = __builtin_amdgcn_mfma_f32_16x16x32_bf16(Bt[n][k], At[m][k], acc[ai][bj][m][n], 0, 0, 0); __builtin_amdgcn_s_setprio(0); } while (0)
; #define PG8_WAIT_V(n) asm volatile("s_waitcnt vmcnt(" #n ")" ::: "memory")
; #define PG8_WAIT_L(n) asm volatile("s_waitcnt lgkmcnt(" #n ")" ::: "memory")
; #define PG8_BAR __builtin_amdgcn_s_barrier()
; #define PG8_SCHED __builtin_amdgcn_sched_barrier(0)
; template <class Epi, class Sched, bool ALIGN_EPI = false, bool SP2 = false, bool GEN = false>
; __device__ __forceinline__ void gemm_phase(PG8_LAS unsigned char* lds, const Gemm g, const Sched& S, const Epi& E, int wave_) {
;     ...
;             PG8_LDB(B0, 0, 0); PG8_LDB(B1, 0, 1); PG8_SCHED; PG8_LDA(At, 0, 0); PG8_STAGE(PG8_SA(1, 1), a1 + hstepA, voffA);
;             PG8_WAIT_V(8); PG8_WAIT_L(0); PG8_BAR; PG8_MMA(0, 0, At, B0); PG8_MMA(0, 1, At, B1); PG8_BAR; PG8_SCHED;
;             PG8_LDA(At, 0, 1); PG8_STAGE(PG8_SB(0, 0), b2, voffB); PG8_STAGE(PG8_SB(0, 1), b2 + hstepB, voffB); PG8_STAGE(PG8_SA(0, 0), a2, voffA);
;             PG8_WAIT_V(8); PG8_WAIT_L(0); PG8_BAR; PG8_MMA(1, 0, At, B0); PG8_MMA(1, 1, At, B1); PG8_BAR; PG8_SCHED;
	s_setprio 1
	s_waitcnt lgkmcnt(0)
	v_mfma_f32_16x16x32_bf16 v[126:129], v[140:143], v[176:179], v[126:129]
	v_mfma_f32_16x16x32_bf16 v[122:125], v[152:155], v[176:179], v[122:125]
	v_mfma_f32_16x16x32_bf16 v[118:121], v[140:143], v[184:187], v[118:121]
	v_mfma_f32_16x16x32_bf16 v[110:113], v[152:155], v[184:187], v[110:113]
	v_mfma_f32_16x16x32_bf16 v[102:105], v[140:143], v[192:195], v[102:105]
	v_mfma_f32_16x16x32_bf16 v[94:97], v[152:155], v[192:195], v[94:97]
	v_mfma_f32_16x16x32_bf16 v[86:89], v[140:143], v[200:203], v[86:89]
	v_mfma_f32_16x16x32_bf16 v[78:81], v[152:155], v[200:203], v[78:81]
	v_mfma_f32_16x16x32_bf16 v[126:129], v[148:151], v[180:183], v[126:129]
	v_mfma_f32_16x16x32_bf16 v[122:125], v[156:159], v[180:183], v[122:125]
	v_mfma_f32_16x16x32_bf16 v[118:121], v[148:151], v[188:191], v[118:121]
	v_mfma_f32_16x16x32_bf16 v[110:113], v[156:159], v[188:191], v[110:113]
	v_mfma_f32_16x16x32_bf16 v[102:105], v[148:151], v[196:199], v[102:105]
	v_mfma_f32_16x16x32_bf16 v[94:97], v[156:159], v[196:199], v[94:97]
	v_mfma_f32_16x16x32_bf16 v[86:89], v[148:151], v[204:207], v[86:89]
	v_mfma_f32_16x16x32_bf16 v[78:81], v[156:159], v[204:207], v[78:81]
	s_setprio 0
	s_setprio 1
	v_mfma_f32_16x16x32_bf16 v[114:117], v[160:163], v[176:179], v[114:117]
	v_mfma_f32_16x16x32_bf16 v[106:109], v[168:171], v[176:179], v[106:109]
	v_mfma_f32_16x16x32_bf16 v[98:101], v[160:163], v[184:187], v[98:101]
	v_mfma_f32_16x16x32_bf16 v[90:93], v[168:171], v[184:187], v[90:93]
	v_mfma_f32_16x16x32_bf16 v[82:85], v[160:163], v[192:195], v[82:85]
	v_mfma_f32_16x16x32_bf16 v[74:77], v[168:171], v[192:195], v[74:77]
	v_mfma_f32_16x16x32_bf16 v[70:73], v[160:163], v[200:203], v[70:73]
	v_mfma_f32_16x16x32_bf16 v[66:69], v[168:171], v[200:203], v[66:69]
	v_mfma_f32_16x16x32_bf16 v[114:117], v[164:167], v[180:183], v[114:117]
	v_mfma_f32_16x16x32_bf16 v[106:109], v[172:175], v[180:183], v[106:109]
	v_mfma_f32_16x16x32_bf16 v[98:101], v[164:167], v[188:191], v[98:101]
	v_mfma_f32_16x16x32_bf16 v[90:93], v[172:175], v[188:191], v[90:93]
	v_mfma_f32_16x16x32_bf16 v[82:85], v[164:167], v[196:199], v[82:85]
	v_mfma_f32_16x16x32_bf16 v[74:77], v[172:175], v[196:199], v[74:77]
	v_mfma_f32_16x16x32_bf16 v[70:73], v[164:167], v[204:207], v[70:73]
	v_mfma_f32_16x16x32_bf16 v[66:69], v[172:175], v[204:207], v[66:69]
	s_setprio 0
	s_barrier
	s_add_i32 s24, s24, s18
	v_lshl_add_u64 v[208:209], s[14:15], 0, v[0:1]
	s_mov_b32 m0, s24
	ds_read_b128 v[176:179], v147 offset:16384
	ds_read_b128 v[180:183], v147 offset:17408
	ds_read_b128 v[184:187], v147 offset:18432
	ds_read_b128 v[188:191], v147 offset:19456
	ds_read_b128 v[192:195], v147 offset:20480
	ds_read_b128 v[196:199], v147 offset:21504
	ds_read_b128 v[200:203], v147 offset:22528
	ds_read_b128 v[204:207], v147 offset:23552
	global_load_lds_dwordx4 v[208:209], off
	s_add_i32 m0, s24, 0x2000
	s_add_u32 s72, s14, 0x100000
	v_lshl_add_u64 v[210:211], s[14:15], 0, v[130:131]
	s_addc_u32 s73, s15, 0
	s_add_i32 s24, s74, s18
	global_load_lds_dwordx4 v[210:211], off
	s_mov_b32 m0, s24
	v_lshl_add_u64 v[214:215], s[28:29], 0, v[132:133]
	global_load_lds_dwordx4 v0, s[72:73]
	s_add_i32 m0, s24, 0x2000
	s_nop 0
	global_load_lds_dwordx4 v130, s[72:73]
	v_lshl_add_u64 v[212:213], s[28:29], 0, v[134:135]
	s_mov_b32 m0, s19
	s_nop 0
	global_load_lds_dwordx4 v[212:213], off
	s_mov_b32 m0, s31
	s_nop 0
	global_load_lds_dwordx4 v[214:215], off
	s_waitcnt vmcnt(8)
	s_waitcnt lgkmcnt(0)
	s_barrier
	s_setprio 1
	s_waitcnt lgkmcnt(0)
	v_mfma_f32_16x16x32_bf16 v[62:65], v[140:143], v[176:179], v[62:65]
	v_mfma_f32_16x16x32_bf16 v[58:61], v[152:155], v[176:179], v[58:61]
	v_mfma_f32_16x16x32_bf16 v[54:57], v[140:143], v[184:187], v[54:57]
	v_mfma_f32_16x16x32_bf16 v[46:49], v[152:155], v[184:187], v[46:49]
	v_mfma_f32_16x16x32_bf16 v[38:41], v[140:143], v[192:195], v[38:41]
	v_mfma_f32_16x16x32_bf16 v[30:33], v[152:155], v[192:195], v[30:33]
	v_mfma_f32_16x16x32_bf16 v[22:25], v[140:143], v[200:203], v[22:25]
	v_mfma_f32_16x16x32_bf16 v[14:17], v[152:155], v[200:203], v[14:17]
	v_mfma_f32_16x16x32_bf16 v[62:65], v[148:151], v[180:183], v[62:65]
	v_mfma_f32_16x16x32_bf16 v[58:61], v[156:159], v[180:183], v[58:61]
	v_mfma_f32_16x16x32_bf16 v[54:57], v[148:151], v[188:191], v[54:57]
	v_mfma_f32_16x16x32_bf16 v[46:49], v[156:159], v[188:191], v[46:49]
	v_mfma_f32_16x16x32_bf16 v[38:41], v[148:151], v[196:199], v[38:41]
	v_mfma_f32_16x16x32_bf16 v[30:33], v[156:159], v[196:199], v[30:33]
	v_mfma_f32_16x16x32_bf16 v[22:25], v[148:151], v[204:207], v[22:25]
	v_mfma_f32_16x16x32_bf16 v[14:17], v[156:159], v[204:207], v[14:17]
	s_setprio 0
	s_setprio 1
	v_mfma_f32_16x16x32_bf16 v[50:53], v[160:163], v[176:179], v[50:53]
	v_mfma_f32_16x16x32_bf16 v[42:45], v[168:171], v[176:179], v[42:45]
	v_mfma_f32_16x16x32_bf16 v[34:37], v[160:163], v[184:187], v[34:37]
	v_mfma_f32_16x16x32_bf16 v[26:29], v[168:171], v[184:187], v[26:29]
	v_mfma_f32_16x16x32_bf16 v[18:21], v[160:163], v[192:195], v[18:21]
	v_mfma_f32_16x16x32_bf16 v[10:13], v[168:171], v[192:195], v[10:13]
	v_mfma_f32_16x16x32_bf16 v[6:9], v[160:163], v[200:203], v[6:9]
	v_mfma_f32_16x16x32_bf16 v[2:5], v[168:171], v[200:203], v[2:5]
	v_mfma_f32_16x16x32_bf16 v[50:53], v[164:167], v[180:183], v[50:53]
	v_mfma_f32_16x16x32_bf16 v[42:45], v[172:175], v[180:183], v[42:45]
	v_mfma_f32_16x16x32_bf16 v[34:37], v[164:167], v[188:191], v[34:37]
	v_mfma_f32_16x16x32_bf16 v[26:29], v[172:175], v[188:191], v[26:29]
	v_mfma_f32_16x16x32_bf16 v[18:21], v[164:167], v[196:199], v[18:21]
	v_mfma_f32_16x16x32_bf16 v[10:13], v[172:175], v[196:199], v[10:13]
	v_mfma_f32_16x16x32_bf16 v[6:9], v[164:167], v[204:207], v[6:9]
	v_mfma_f32_16x16x32_bf16 v[2:5], v[172:175], v[204:207], v[2:5]
	s_setprio 0
	s_barrier
; #define PG8_STAGE(bufoff, gbase, voff) do { _Pragma("unroll") for (int _i = 0; _i < 2; ++_i) \
;         __builtin_amdgcn_global_load_lds((const unsigned*)((const char*)(gbase) + (voff)[_i]), (PG8_LAS unsigned*)(lds + (bufoff) + ldsw + _i * 8192), 16, 0, 0); } while (0)
; #define PG8_LDA(dst, b, h) do { _Pragma("unroll") for (int m = 0; m < 4; ++m) _Pragma("unroll") for (int k = 0; k < 2; ++k) dst[m][k] = *(const PG8_LAS bf16x8*)(lds + PG8_SA(b, h) + aoff + m * 2048 + k * 1024); } while (0)
; #define PG8_LDB(dst, b, h) do { _Pragma("unroll") for (int n = 0; n < 2; ++n) _Pragma("unroll") for (int k = 0; k < 2; ++k) dst[n][k] = *(const PG8_LAS bf16x8*)(lds + PG8_SB(b, h) + boff + n * 2048 + k * 1024); } while (0)
; #define PG8_MMA(ai, bj, At, Bt) do { __builtin_amdgcn_s_setprio(1); _Pragma("unroll") for (int m = 0; m < 4; ++m) _Pragma("unroll") for (int n = 0; n < 2; ++n) _Pragma("unroll") for (int k = 0; k < 2; ++k) \
;         acc[ai][bj][m][n] = __builtin_amdgcn_mfma_f32_16x16x32_bf16(Bt[n][k], At[m][k], acc[ai][bj][m][n], 0, 0, 0); __builtin_amdgcn_s_setprio(0); } while (0)
; #define PG8_WAIT_V(n) asm volatile("s_waitcnt vmcnt(" #n ")" ::: "memory")
; #define PG8_WAIT_L(n) asm volatile("s_waitcnt lgkmcnt(" #n ")" ::: "memory")
; #define PG8_BAR __builtin_amdgcn_s_barrier()
; #define PG8_SCHED __builtin_amdgcn_sched_barrier(0)
; template <class Epi, class Sched, bool ALIGN_EPI = false, bool SP2 = false, bool GEN = false>
; __device__ __forceinline__ void gemm_phase(PG8_LAS unsigned char* lds, const Gemm g, const Sched& S, const Epi& E, int wave_) {
;     ...
;             PG8_LDB(B0, 1, 0); PG8_LDB(B1, 1, 1); PG8_SCHED; PG8_LDA(At, 1, 0); PG8_STAGE(PG8_SA(0, 1), a2 + hstepA, voffA);
;             PG8_WAIT_V(8); PG8_WAIT_L(0); PG8_BAR; PG8_MMA(0, 0, At, B0); PG8_MMA(0, 1, At, B1); PG8_BAR; PG8_SCHED;
;             PG8_LDA(At, 1, 1); PG8_STAGE(PG8_SB(1, 0), b3, voffB); PG8_STAGE(PG8_SB(1, 1), b3 + hstepB, voffB); PG8_STAGE(PG8_SA(1, 0), a3, voffA);
;             PG8_WAIT_V(8); PG8_WAIT_L(0); PG8_BAR; PG8_MMA(1, 0, At, B0); PG8_MMA(1, 1, At, B1); PG8_BAR; PG8_SCHED;
	s_add_i32 s24, 0, 0x18000
	s_add_i32 s72, 0, 0x1c000
	v_add_u32_e32 v156, s24, v145
	v_add_u32_e32 v172, s72, v145
	ds_read_b128 v[140:143], v156
	ds_read_b128 v[148:151], v156 offset:1024
	ds_read_b128 v[152:155], v156 offset:2048
	ds_read_b128 v[156:159], v156 offset:3072
	ds_read_b128 v[160:163], v172
	ds_read_b128 v[164:167], v172 offset:1024
	ds_read_b128 v[168:171], v172 offset:2048
	ds_read_b128 v[172:175], v172 offset:3072
	s_add_u32 s28, s28, 0x100000
	s_addc_u32 s29, s29, 0
	s_mov_b32 m0, s38
	ds_read_b128 v[176:179], v147 offset:32768
	ds_read_b128 v[180:183], v147 offset:33792
	ds_read_b128 v[184:187], v147 offset:34816
	ds_read_b128 v[188:191], v147 offset:35840
	ds_read_b128 v[192:195], v147 offset:36864
	ds_read_b128 v[196:199], v147 offset:37888
	ds_read_b128 v[200:203], v147 offset:38912
	ds_read_b128 v[204:207], v147 offset:39936
	global_load_lds_dwordx4 v134, s[28:29]
	s_mov_b32 m0, s39
	s_nop 0
	global_load_lds_dwordx4 v132, s[28:29]
	s_waitcnt vmcnt(8)
	s_waitcnt lgkmcnt(0)
	s_barrier
	s_setprio 1
	s_waitcnt lgkmcnt(0)
	v_mfma_f32_16x16x32_bf16 v[126:129], v[140:143], v[176:179], v[126:129]
	v_mfma_f32_16x16x32_bf16 v[122:125], v[152:155], v[176:179], v[122:125]
	v_mfma_f32_16x16x32_bf16 v[118:121], v[140:143], v[184:187], v[118:121]
	v_mfma_f32_16x16x32_bf16 v[110:113], v[152:155], v[184:187], v[110:113]
	v_mfma_f32_16x16x32_bf16 v[102:105], v[140:143], v[192:195], v[102:105]
	v_mfma_f32_16x16x32_bf16 v[94:97], v[152:155], v[192:195], v[94:97]
	v_mfma_f32_16x16x32_bf16 v[86:89], v[140:143], v[200:203], v[86:89]
	v_mfma_f32_16x16x32_bf16 v[78:81], v[152:155], v[200:203], v[78:81]
	v_mfma_f32_16x16x32_bf16 v[126:129], v[148:151], v[180:183], v[126:129]
	v_mfma_f32_16x16x32_bf16 v[122:125], v[156:159], v[180:183], v[122:125]
	v_mfma_f32_16x16x32_bf16 v[118:121], v[148:151], v[188:191], v[118:121]
	v_mfma_f32_16x16x32_bf16 v[110:113], v[156:159], v[188:191], v[110:113]
	v_mfma_f32_16x16x32_bf16 v[102:105], v[148:151], v[196:199], v[102:105]
	v_mfma_f32_16x16x32_bf16 v[94:97], v[156:159], v[196:199], v[94:97]
	v_mfma_f32_16x16x32_bf16 v[86:89], v[148:151], v[204:207], v[86:89]
	v_mfma_f32_16x16x32_bf16 v[78:81], v[156:159], v[204:207], v[78:81]
	s_setprio 0
	s_setprio 1
	v_mfma_f32_16x16x32_bf16 v[114:117], v[160:163], v[176:179], v[114:117]
	v_mfma_f32_16x16x32_bf16 v[106:109], v[168:171], v[176:179], v[106:109]
	v_mfma_f32_16x16x32_bf16 v[98:101], v[160:163], v[184:187], v[98:101]
	v_mfma_f32_16x16x32_bf16 v[90:93], v[168:171], v[184:187], v[90:93]
	v_mfma_f32_16x16x32_bf16 v[82:85], v[160:163], v[192:195], v[82:85]
	v_mfma_f32_16x16x32_bf16 v[74:77], v[168:171], v[192:195], v[74:77]
	v_mfma_f32_16x16x32_bf16 v[70:73], v[160:163], v[200:203], v[70:73]
	v_mfma_f32_16x16x32_bf16 v[66:69], v[168:171], v[200:203], v[66:69]
	v_mfma_f32_16x16x32_bf16 v[114:117], v[164:167], v[180:183], v[114:117]
	v_mfma_f32_16x16x32_bf16 v[106:109], v[172:175], v[180:183], v[106:109]
	v_mfma_f32_16x16x32_bf16 v[98:101], v[164:167], v[188:191], v[98:101]
	v_mfma_f32_16x16x32_bf16 v[90:93], v[172:175], v[188:191], v[90:93]
	v_mfma_f32_16x16x32_bf16 v[82:85], v[164:167], v[196:199], v[82:85]
	v_mfma_f32_16x16x32_bf16 v[74:77], v[172:175], v[196:199], v[74:77]
	v_mfma_f32_16x16x32_bf16 v[70:73], v[164:167], v[204:207], v[70:73]
	v_mfma_f32_16x16x32_bf16 v[66:69], v[172:175], v[204:207], v[66:69]
	s_setprio 0
	s_barrier
	s_add_i32 s24, s24, s18
	v_lshl_add_u64 v[208:209], v[208:209], 0, s[76:77]
	s_mov_b32 m0, s24
	ds_read_b128 v[176:179], v147 offset:49152
	ds_read_b128 v[180:183], v147 offset:50176
	ds_read_b128 v[184:187], v147 offset:51200
	ds_read_b128 v[188:191], v147 offset:52224
	ds_read_b128 v[192:195], v147 offset:53248
	ds_read_b128 v[196:199], v147 offset:54272
	ds_read_b128 v[200:203], v147 offset:55296
	ds_read_b128 v[204:207], v147 offset:56320
	global_load_lds_dwordx4 v[208:209], off
	s_add_i32 m0, s24, 0x2000
	s_add_u32 s14, s14, 0x100080
	v_lshl_add_u64 v[208:209], v[210:211], 0, s[76:77]
	s_addc_u32 s15, s15, 0
	s_add_i32 s24, s72, s18
	global_load_lds_dwordx4 v[208:209], off
	s_mov_b32 m0, s24
	s_nop 0
	global_load_lds_dwordx4 v0, s[14:15]
	s_add_i32 m0, s24, 0x2000
	s_nop 0
	global_load_lds_dwordx4 v130, s[14:15]
	v_lshl_add_u64 v[208:209], v[212:213], 0, s[76:77]
	s_mov_b32 m0, s60
	s_nop 0
	global_load_lds_dwordx4 v[208:209], off
	v_lshl_add_u64 v[208:209], v[214:215], 0, s[76:77]
	s_mov_b32 m0, s61
	s_nop 0
	global_load_lds_dwordx4 v[208:209], off
	s_waitcnt vmcnt(8)
	s_waitcnt lgkmcnt(0)
	s_barrier
	s_setprio 1
	s_waitcnt lgkmcnt(0)
	v_mfma_f32_16x16x32_bf16 v[62:65], v[140:143], v[176:179], v[62:65]
	v_mfma_f32_16x16x32_bf16 v[58:61], v[152:155], v[176:179], v[58:61]
	v_mfma_f32_16x16x32_bf16 v[54:57], v[140:143], v[184:187], v[54:57]
	v_mfma_f32_16x16x32_bf16 v[46:49], v[152:155], v[184:187], v[46:49]
	v_mfma_f32_16x16x32_bf16 v[38:41], v[140:143], v[192:195], v[38:41]
	v_mfma_f32_16x16x32_bf16 v[30:33], v[152:155], v[192:195], v[30:33]
	v_mfma_f32_16x16x32_bf16 v[22:25], v[140:143], v[200:203], v[22:25]
	v_mfma_f32_16x16x32_bf16 v[14:17], v[152:155], v[200:203], v[14:17]
	v_mfma_f32_16x16x32_bf16 v[62:65], v[148:151], v[180:183], v[62:65]
	v_mfma_f32_16x16x32_bf16 v[58:61], v[156:159], v[180:183], v[58:61]
	v_mfma_f32_16x16x32_bf16 v[54:57], v[148:151], v[188:191], v[54:57]
	v_mfma_f32_16x16x32_bf16 v[46:49], v[156:159], v[188:191], v[46:49]
	v_mfma_f32_16x16x32_bf16 v[38:41], v[148:151], v[196:199], v[38:41]
	v_mfma_f32_16x16x32_bf16 v[30:33], v[156:159], v[196:199], v[30:33]
	v_mfma_f32_16x16x32_bf16 v[22:25], v[148:151], v[204:207], v[22:25]
	v_mfma_f32_16x16x32_bf16 v[14:17], v[156:159], v[204:207], v[14:17]
	s_setprio 0
	s_setprio 1
	v_mfma_f32_16x16x32_bf16 v[50:53], v[160:163], v[176:179], v[50:53]
	v_mfma_f32_16x16x32_bf16 v[42:45], v[168:171], v[176:179], v[42:45]
	v_mfma_f32_16x16x32_bf16 v[34:37], v[160:163], v[184:187], v[34:37]
	v_mfma_f32_16x16x32_bf16 v[26:29], v[168:171], v[184:187], v[26:29]
	v_mfma_f32_16x16x32_bf16 v[18:21], v[160:163], v[192:195], v[18:21]
	v_mfma_f32_16x16x32_bf16 v[10:13], v[168:171], v[192:195], v[10:13]
	v_mfma_f32_16x16x32_bf16 v[6:9], v[160:163], v[200:203], v[6:9]
	v_mfma_f32_16x16x32_bf16 v[2:5], v[168:171], v[200:203], v[2:5]
	v_mfma_f32_16x16x32_bf16 v[50:53], v[164:167], v[180:183], v[50:53]
	v_mfma_f32_16x16x32_bf16 v[42:45], v[172:175], v[180:183], v[42:45]
	v_mfma_f32_16x16x32_bf16 v[34:37], v[164:167], v[188:191], v[34:37]
	v_mfma_f32_16x16x32_bf16 v[26:29], v[172:175], v[188:191], v[26:29]
	v_mfma_f32_16x16x32_bf16 v[18:21], v[164:167], v[196:199], v[18:21]
	v_mfma_f32_16x16x32_bf16 v[10:13], v[172:175], v[196:199], v[10:13]
	v_mfma_f32_16x16x32_bf16 v[6:9], v[164:167], v[204:207], v[6:9]
	v_mfma_f32_16x16x32_bf16 v[2:5], v[172:175], v[204:207], v[2:5]
	s_setprio 0
	s_barrier
	s_cmp_gt_i32 s67, 59
	s_cbranch_scc0 .LBB0_110
	s_and_b64 vcc, exec, s[48:49]
	s_cbranch_vccz .LBB0_113
	s_barrier

; #define PG8_STAGE(bufoff, gbase, voff) do { _Pragma("unroll") for (int _i = 0; _i < 2; ++_i) \
;         __builtin_amdgcn_global_load_lds((const unsigned*)((const char*)(gbase) + (voff)[_i]), (PG8_LAS unsigned*)(lds + (bufoff) + ldsw + _i * 8192), 16, 0, 0); } while (0)
; #define PG8_LDA(dst, b, h) do { _Pragma("unroll") for (int m = 0; m < 4; ++m) _Pragma("unroll") for (int k = 0; k < 2; ++k) dst[m][k] = *(const PG8_LAS bf16x8*)(lds + PG8_SA(b, h) + aoff + m * 2048 + k * 1024); } while (0)
; #define PG8_LDB(dst, b, h) do { _Pragma("unroll") for (int n = 0; n < 2; ++n) _Pragma("unroll") for (int k = 0; k < 2; ++k) dst[n][k] = *(const PG8_LAS bf16x8*)(lds + PG8_SB(b, h) + boff + n * 2048 + k * 1024); } while (0)
; #define PG8_SCHED __builtin_amdgcn_sched_barrier(0)
; template <class Epi, class Sched, bool ALIGN_EPI = false, bool SP2 = false, bool GEN = false>
; __device__ __forceinline__ void gemm_phase(PG8_LAS unsigned char* lds, const Gemm g, const Sched& S, const Epi& E, int wave_) {
;     ...
;         const bool has_next = S.next(ui + 1, nxt);
;         const char* nA = has_next ? (const char*)g.A + (size_t)nxt.pm * tstepA + (GEN ? S.acol(nxt) * 2 : 0) : cA; const char* nB = has_next ? (const char*)g.Bt + (size_t)nxt.pn * tstepB : cB;
;         for (int t = 0; t < nt; t += 2) {
;             const bool last = (t == nt - 2);
;             const char* a1 = cA + (size_t)(t + 1) * kstep;
;             const char* a2 = last ? nA : cA + (size_t)(t + 2) * kstep; const char* b2 = last ? nB : cB + (size_t)(t + 2) * kstep;
;             const char* a3 = a2 + kstep; const char* b3 = b2 + kstep;
;             if (last && has_next) S.a_ready(nxt);
;             if constexpr (SP2) {
;             PG8_LDB(B0, 0, 0); PG8_LDB(B1, 0, 1); PG8_SCHED; PG8_LDA(At, 0, 0); PG8_STAGE(PG8_SA(1, 1), a1 + hstepA, voffA);
;     ...
;         for (int a = 0; a < 2; ++a)
; #pragma unroll
;             for (int b = 0; b < 2; ++b)
; #pragma unroll
;                 for (int m = 0; m < 4; ++m)
; #pragma unroll
;                     for (int n = 0; n < 2; ++n) acc[a][b][m][n] = (f32x4){0.f, 0.f, 0.f, 0.f};
;         cur = nxt; cA = nA; cB = nB; ++ui;
.LBB0_944:
	s_ashr_i32 s57, s56, 31
	s_lshl_b64 s[14:15], s[56:57], 21
	s_add_u32 s58, s34, s14
	s_addc_u32 s59, s35, s15
	s_and_b64 s[14:15], s[42:43], exec
	s_cselect_b32 s57, s59, s39
	s_cselect_b32 s73, s58, s38
	s_ashr_i32 s55, s54, 31
	s_lshl_b64 s[14:15], s[54:55], 21
	s_add_u32 s60, s44, s14
	s_addc_u32 s61, s45, s15
	s_and_b64 s[14:15], s[42:43], exec
	s_cselect_b32 s55, s61, s29
	s_cselect_b32 s74, s60, s28
	s_add_u32 s75, s28, 0x100
	s_addc_u32 s78, s29, 0
	s_add_u32 s62, s38, 0x100080
	v_mov_b32_e32 v2, 0
	s_addc_u32 s63, s39, 0
	s_mov_b32 s38, -2
	v_mov_b32_e32 v3, v2
	v_mov_b32_e32 v4, v2
	v_mov_b32_e32 v5, v2
	v_mov_b32_e32 v6, v2
	v_mov_b32_e32 v7, v2
	v_mov_b32_e32 v8, v2
	v_mov_b32_e32 v9, v2
	v_mov_b32_e32 v18, v2
	v_mov_b32_e32 v19, v2
	v_mov_b32_e32 v20, v2
	v_mov_b32_e32 v21, v2
	v_mov_b32_e32 v22, v2
	v_mov_b32_e32 v23, v2
	v_mov_b32_e32 v24, v2
	v_mov_b32_e32 v25, v2
	v_mov_b32_e32 v34, v2
	v_mov_b32_e32 v35, v2
	v_mov_b32_e32 v36, v2
	v_mov_b32_e32 v37, v2
	v_mov_b32_e32 v38, v2
	v_mov_b32_e32 v39, v2
	v_mov_b32_e32 v40, v2
	v_mov_b32_e32 v41, v2
	v_mov_b32_e32 v50, v2
	v_mov_b32_e32 v51, v2
	v_mov_b32_e32 v52, v2
	v_mov_b32_e32 v53, v2
	v_mov_b32_e32 v54, v2
	v_mov_b32_e32 v55, v2
	v_mov_b32_e32 v56, v2
	v_mov_b32_e32 v57, v2
	v_mov_b32_e32 v10, v2
	v_mov_b32_e32 v11, v2
	v_mov_b32_e32 v12, v2
	v_mov_b32_e32 v13, v2
	v_mov_b32_e32 v14, v2
	v_mov_b32_e32 v15, v2
	v_mov_b32_e32 v16, v2
	v_mov_b32_e32 v17, v2
	v_mov_b32_e32 v26, v2
	v_mov_b32_e32 v27, v2
	v_mov_b32_e32 v28, v2
	v_mov_b32_e32 v29, v2
	v_mov_b32_e32 v30, v2
	v_mov_b32_e32 v31, v2
	v_mov_b32_e32 v32, v2
	v_mov_b32_e32 v33, v2
	v_mov_b32_e32 v42, v2
	v_mov_b32_e32 v43, v2
	v_mov_b32_e32 v44, v2
	v_mov_b32_e32 v45, v2
	v_mov_b32_e32 v46, v2
	v_mov_b32_e32 v47, v2
	v_mov_b32_e32 v48, v2
	v_mov_b32_e32 v49, v2
	v_mov_b32_e32 v58, v2
	v_mov_b32_e32 v59, v2
	v_mov_b32_e32 v60, v2
	v_mov_b32_e32 v61, v2
	v_mov_b32_e32 v62, v2
	v_mov_b32_e32 v63, v2
	v_mov_b32_e32 v64, v2
	v_mov_b32_e32 v65, v2
	v_mov_b32_e32 v66, v2
	v_mov_b32_e32 v67, v2
	v_mov_b32_e32 v68, v2
	v_mov_b32_e32 v69, v2
	v_mov_b32_e32 v70, v2
	v_mov_b32_e32 v71, v2
	v_mov_b32_e32 v72, v2
	v_mov_b32_e32 v73, v2
	v_mov_b32_e32 v82, v2
	v_mov_b32_e32 v83, v2
	v_mov_b32_e32 v84, v2
	v_mov_b32_e32 v85, v2
	v_mov_b32_e32 v86, v2
	v_mov_b32_e32 v87, v2
	v_mov_b32_e32 v88, v2
	v_mov_b32_e32 v89, v2
	v_mov_b32_e32 v98, v2
	v_mov_b32_e32 v99, v2
	v_mov_b32_e32 v100, v2
	v_mov_b32_e32 v101, v2
	v_mov_b32_e32 v102, v2
	v_mov_b32_e32 v103, v2
	v_mov_b32_e32 v104, v2
	v_mov_b32_e32 v105, v2
	v_mov_b32_e32 v114, v2
	v_mov_b32_e32 v115, v2
	v_mov_b32_e32 v116, v2
	v_mov_b32_e32 v117, v2
	v_mov_b32_e32 v118, v2
	v_mov_b32_e32 v119, v2
	v_mov_b32_e32 v120, v2
	v_mov_b32_e32 v121, v2
	v_mov_b32_e32 v74, v2
	v_mov_b32_e32 v75, v2
	v_mov_b32_e32 v76, v2
	v_mov_b32_e32 v77, v2
	v_mov_b32_e32 v78, v2
	v_mov_b32_e32 v79, v2
	v_mov_b32_e32 v80, v2
	v_mov_b32_e32 v81, v2
	v_mov_b32_e32 v90, v2
	v_mov_b32_e32 v91, v2
	v_mov_b32_e32 v92, v2
	v_mov_b32_e32 v93, v2
	v_mov_b32_e32 v94, v2
	v_mov_b32_e32 v95, v2
	v_mov_b32_e32 v96, v2
	v_mov_b32_e32 v97, v2
	v_mov_b32_e32 v106, v2
	v_mov_b32_e32 v107, v2
	v_mov_b32_e32 v108, v2
	v_mov_b32_e32 v109, v2
	v_mov_b32_e32 v110, v2
	v_mov_b32_e32 v111, v2
	v_mov_b32_e32 v112, v2
	v_mov_b32_e32 v113, v2
	v_mov_b32_e32 v122, v2
	v_mov_b32_e32 v123, v2
	v_mov_b32_e32 v124, v2
	v_mov_b32_e32 v125, v2
	v_mov_b32_e32 v126, v2
	v_mov_b32_e32 v127, v2
	v_mov_b32_e32 v128, v2
	v_mov_b32_e32 v129, v2
	s_add_i32 s38, s38, -2
	s_sub_u32 s75, s75, 0x100
	s_subb_u32 s78, s78, 0
	s_sub_u32 s62, s62, 0x100
	s_subb_u32 s63, s63, 0
.LBB0_945:
	v_add_u32_e32 v144, 0x10000, v147
	ds_read_b128 v[140:143], v144
	ds_read_b128 v[150:153], v144 offset:1024
	ds_read_b128 v[154:157], v144 offset:2048
	ds_read_b128 v[158:161], v144 offset:3072
	v_add_u32_e32 v144, 0x14000, v147
	ds_read_b128 v[162:165], v144
	ds_read_b128 v[166:169], v144 offset:1024
	ds_read_b128 v[170:173], v144 offset:2048
	ds_read_b128 v[174:177], v144 offset:3072
	s_add_i32 m0, s19, 0xc000
	ds_read_b128 v[178:181], v149
	ds_read_b128 v[182:185], v149 offset:1024
	ds_read_b128 v[186:189], v149 offset:2048
	ds_read_b128 v[190:193], v149 offset:3072
	ds_read_b128 v[194:197], v149 offset:4096
	ds_read_b128 v[198:201], v149 offset:5120
	ds_read_b128 v[202:205], v149 offset:6144
	ds_read_b128 v[206:209], v149 offset:7168
	s_add_i32 s38, s38, 2
	s_add_u32 s75, s75, 0x100
	s_addc_u32 s78, s78, 0
	s_add_u32 s62, s62, 0x100
	s_addc_u32 s63, s63, 0
	global_load_lds_dwordx4 v138, s[62:63]
	s_add_i32 m0, s19, 0xe000
	s_nop 0
	global_load_lds_dwordx4 v136, s[62:63]
	s_add_i32 s24, 0, 0x10000
	s_add_i32 s39, 0, 0x14000
	s_add_u32 s14, s62, 0xfff00080
	s_addc_u32 s15, s63, -1
	s_cmp_eq_u32 s38, 60
	s_cselect_b32 s29, s57, s15
	s_cselect_b32 s28, s73, s14
	s_cselect_b32 s15, s55, s78
	s_cselect_b32 s14, s74, s75
	s_waitcnt vmcnt(8)
	s_waitcnt lgkmcnt(0)
	s_barrier
; #define PG8_STAGE(bufoff, gbase, voff) do { _Pragma("unroll") for (int _i = 0; _i < 2; ++_i) \
;         __builtin_amdgcn_global_load_lds((const unsigned*)((const char*)(gbase) + (voff)[_i]), (PG8_LAS unsigned*)(lds + (bufoff) + ldsw + _i * 8192), 16, 0, 0); } while (0)
; #define PG8_LDA(dst, b, h) do { _Pragma("unroll") for (int m = 0; m < 4; ++m) _Pragma("unroll") for (int k = 0; k < 2; ++k) dst[m][k] = *(const PG8_LAS bf16x8*)(lds + PG8_SA(b, h) + aoff + m * 2048 + k * 1024); } while (0)
; #define PG8_MMA(ai, bj, At, Bt) do { __builtin_amdgcn_s_setprio(1); _Pragma("unroll") for (int m = 0; m < 4; ++m) _Pragma("unroll") for (int n = 0; n < 2; ++n) _Pragma("unroll") for (int k = 0; k < 2; ++k) \
;         acc[ai][bj][m][n] = __builtin_amdgcn_mfma_f32_16x16x32_bf16(Bt[n][k], At[m][k], acc[ai][bj][m][n], 0, 0, 0); __builtin_amdgcn_s_setprio(0); } while (0)
; #define PG8_WAIT_V(n) asm volatile("s_waitcnt vmcnt(" #n ")" ::: "memory")
; #define PG8_WAIT_L(n) asm volatile("s_waitcnt lgkmcnt(" #n ")" ::: "memory")
; #define PG8_BAR __builtin_amdgcn_s_barrier()
; #define PG8_SCHED __builtin_amdgcn_sched_barrier(0)
; template <class Epi, class Sched, bool ALIGN_EPI = false, bool SP2 = false, bool GEN = false>
; __device__ __forceinline__ void gemm_phase(PG8_LAS unsigned char* lds, const Gemm g, const Sched& S, const Epi& E, int wave_) {
;     ...
;             PG8_WAIT_V(8); PG8_WAIT_L(0); PG8_BAR; PG8_MMA(0, 0, At, B0); PG8_MMA(0, 1, At, B1); PG8_BAR; PG8_SCHED;
;             PG8_LDA(At, 0, 1); PG8_STAGE(PG8_SB(0, 0), b2, voffB); PG8_STAGE(PG8_SB(0, 1), b2 + hstepB, voffB); PG8_STAGE(PG8_SA(0, 0), a2, voffA);
;             PG8_WAIT_V(8); PG8_WAIT_L(0); PG8_BAR; PG8_MMA(1, 0, At, B0); PG8_MMA(1, 1, At, B1); PG8_BAR; PG8_SCHED;
	s_setprio 1
	s_waitcnt lgkmcnt(0)
	v_mfma_f32_16x16x32_bf16 v[126:129], v[140:143], v[178:181], v[126:129]
	v_mfma_f32_16x16x32_bf16 v[122:125], v[154:157], v[178:181], v[122:125]
	v_mfma_f32_16x16x32_bf16 v[110:113], v[140:143], v[186:189], v[110:113]
	v_mfma_f32_16x16x32_bf16 v[106:109], v[154:157], v[186:189], v[106:109]
	v_mfma_f32_16x16x32_bf16 v[94:97], v[140:143], v[194:197], v[94:97]
	v_mfma_f32_16x16x32_bf16 v[90:93], v[154:157], v[194:197], v[90:93]
	v_mfma_f32_16x16x32_bf16 v[78:81], v[140:143], v[202:205], v[78:81]
	v_mfma_f32_16x16x32_bf16 v[74:77], v[154:157], v[202:205], v[74:77]
	v_mfma_f32_16x16x32_bf16 v[126:129], v[150:153], v[182:185], v[126:129]
	v_mfma_f32_16x16x32_bf16 v[122:125], v[158:161], v[182:185], v[122:125]
	v_mfma_f32_16x16x32_bf16 v[110:113], v[150:153], v[190:193], v[110:113]
	v_mfma_f32_16x16x32_bf16 v[106:109], v[158:161], v[190:193], v[106:109]
	v_mfma_f32_16x16x32_bf16 v[94:97], v[150:153], v[198:201], v[94:97]
	v_mfma_f32_16x16x32_bf16 v[90:93], v[158:161], v[198:201], v[90:93]
	v_mfma_f32_16x16x32_bf16 v[78:81], v[150:153], v[206:209], v[78:81]
	v_mfma_f32_16x16x32_bf16 v[74:77], v[158:161], v[206:209], v[74:77]
	s_setprio 0
	s_setprio 1
	v_mfma_f32_16x16x32_bf16 v[118:121], v[162:165], v[178:181], v[118:121]
	v_mfma_f32_16x16x32_bf16 v[114:117], v[170:173], v[178:181], v[114:117]
	v_mfma_f32_16x16x32_bf16 v[102:105], v[162:165], v[186:189], v[102:105]
	v_mfma_f32_16x16x32_bf16 v[98:101], v[170:173], v[186:189], v[98:101]
	v_mfma_f32_16x16x32_bf16 v[86:89], v[162:165], v[194:197], v[86:89]
	v_mfma_f32_16x16x32_bf16 v[82:85], v[170:173], v[194:197], v[82:85]
	v_mfma_f32_16x16x32_bf16 v[70:73], v[162:165], v[202:205], v[70:73]
	v_mfma_f32_16x16x32_bf16 v[66:69], v[170:173], v[202:205], v[66:69]
	v_mfma_f32_16x16x32_bf16 v[118:121], v[166:169], v[182:185], v[118:121]
	v_mfma_f32_16x16x32_bf16 v[114:117], v[174:177], v[182:185], v[114:117]
	v_mfma_f32_16x16x32_bf16 v[102:105], v[166:169], v[190:193], v[102:105]
	v_mfma_f32_16x16x32_bf16 v[98:101], v[174:177], v[190:193], v[98:101]
	v_mfma_f32_16x16x32_bf16 v[86:89], v[166:169], v[198:201], v[86:89]
	v_mfma_f32_16x16x32_bf16 v[82:85], v[174:177], v[198:201], v[82:85]
	v_mfma_f32_16x16x32_bf16 v[70:73], v[166:169], v[206:209], v[70:73]
	v_mfma_f32_16x16x32_bf16 v[66:69], v[174:177], v[206:209], v[66:69]
	s_setprio 0
	s_barrier
	s_add_i32 s24, s24, s18
	v_lshl_add_u64 v[144:145], s[14:15], 0, v[0:1]
	s_mov_b32 m0, s24
	ds_read_b128 v[178:181], v149 offset:16384
	ds_read_b128 v[182:185], v149 offset:17408
	ds_read_b128 v[186:189], v149 offset:18432
	ds_read_b128 v[190:193], v149 offset:19456
	ds_read_b128 v[194:197], v149 offset:20480
	ds_read_b128 v[198:201], v149 offset:21504
	ds_read_b128 v[202:205], v149 offset:22528
	ds_read_b128 v[206:209], v149 offset:23552
	global_load_lds_dwordx4 v[144:145], off
	s_add_i32 m0, s24, 0x2000
	s_add_u32 s80, s14, 0x100000
	v_lshl_add_u64 v[210:211], s[14:15], 0, v[130:131]
	s_addc_u32 s81, s15, 0
	s_add_i32 s24, s39, s18
	global_load_lds_dwordx4 v[210:211], off
	s_mov_b32 m0, s24
	v_lshl_add_u64 v[214:215], s[28:29], 0, v[132:133]
	global_load_lds_dwordx4 v0, s[80:81]
	s_add_i32 m0, s24, 0x2000
	s_nop 0
	global_load_lds_dwordx4 v130, s[80:81]
	v_lshl_add_u64 v[212:213], s[28:29], 0, v[134:135]
	s_mov_b32 m0, s19
	s_nop 0
	global_load_lds_dwordx4 v[212:213], off
	s_mov_b32 m0, s31
	s_nop 0
	global_load_lds_dwordx4 v[214:215], off
	s_waitcnt vmcnt(8)
	s_waitcnt lgkmcnt(0)
	s_barrier
	s_setprio 1
	s_waitcnt lgkmcnt(0)
	v_mfma_f32_16x16x32_bf16 v[62:65], v[140:143], v[178:181], v[62:65]
	v_mfma_f32_16x16x32_bf16 v[58:61], v[154:157], v[178:181], v[58:61]
	v_mfma_f32_16x16x32_bf16 v[46:49], v[140:143], v[186:189], v[46:49]
	v_mfma_f32_16x16x32_bf16 v[42:45], v[154:157], v[186:189], v[42:45]
	v_mfma_f32_16x16x32_bf16 v[30:33], v[140:143], v[194:197], v[30:33]
	v_mfma_f32_16x16x32_bf16 v[26:29], v[154:157], v[194:197], v[26:29]
	v_mfma_f32_16x16x32_bf16 v[14:17], v[140:143], v[202:205], v[14:17]
	v_mfma_f32_16x16x32_bf16 v[10:13], v[154:157], v[202:205], v[10:13]
	v_mfma_f32_16x16x32_bf16 v[62:65], v[150:153], v[182:185], v[62:65]
	v_mfma_f32_16x16x32_bf16 v[58:61], v[158:161], v[182:185], v[58:61]
	v_mfma_f32_16x16x32_bf16 v[46:49], v[150:153], v[190:193], v[46:49]
	v_mfma_f32_16x16x32_bf16 v[42:45], v[158:161], v[190:193], v[42:45]
	v_mfma_f32_16x16x32_bf16 v[30:33], v[150:153], v[198:201], v[30:33]
	v_mfma_f32_16x16x32_bf16 v[26:29], v[158:161], v[198:201], v[26:29]
	v_mfma_f32_16x16x32_bf16 v[14:17], v[150:153], v[206:209], v[14:17]
	v_mfma_f32_16x16x32_bf16 v[10:13], v[158:161], v[206:209], v[10:13]
	s_setprio 0
	s_setprio 1
	v_mfma_f32_16x16x32_bf16 v[54:57], v[162:165], v[178:181], v[54:57]
	v_mfma_f32_16x16x32_bf16 v[50:53], v[170:173], v[178:181], v[50:53]
	v_mfma_f32_16x16x32_bf16 v[38:41], v[162:165], v[186:189], v[38:41]
	v_mfma_f32_16x16x32_bf16 v[34:37], v[170:173], v[186:189], v[34:37]
	v_mfma_f32_16x16x32_bf16 v[22:25], v[162:165], v[194:197], v[22:25]
	v_mfma_f32_16x16x32_bf16 v[18:21], v[170:173], v[194:197], v[18:21]
	v_mfma_f32_16x16x32_bf16 v[6:9], v[162:165], v[202:205], v[6:9]
	v_mfma_f32_16x16x32_bf16 v[2:5], v[170:173], v[202:205], v[2:5]
	v_mfma_f32_16x16x32_bf16 v[54:57], v[166:169], v[182:185], v[54:57]
	v_mfma_f32_16x16x32_bf16 v[50:53], v[174:177], v[182:185], v[50:53]
	v_mfma_f32_16x16x32_bf16 v[38:41], v[166:169], v[190:193], v[38:41]
	v_mfma_f32_16x16x32_bf16 v[34:37], v[174:177], v[190:193], v[34:37]
	v_mfma_f32_16x16x32_bf16 v[22:25], v[166:169], v[198:201], v[22:25]
	v_mfma_f32_16x16x32_bf16 v[18:21], v[174:177], v[198:201], v[18:21]
	v_mfma_f32_16x16x32_bf16 v[6:9], v[166:169], v[206:209], v[6:9]
	v_mfma_f32_16x16x32_bf16 v[2:5], v[174:177], v[206:209], v[2:5]
	s_setprio 0
	s_barrier
; #define PG8_STAGE(bufoff, gbase, voff) do { _Pragma("unroll") for (int _i = 0; _i < 2; ++_i) \
;         __builtin_amdgcn_global_load_lds((const unsigned*)((const char*)(gbase) + (voff)[_i]), (PG8_LAS unsigned*)(lds + (bufoff) + ldsw + _i * 8192), 16, 0, 0); } while (0)
; #define PG8_LDA(dst, b, h) do { _Pragma("unroll") for (int m = 0; m < 4; ++m) _Pragma("unroll") for (int k = 0; k < 2; ++k) dst[m][k] = *(const PG8_LAS bf16x8*)(lds + PG8_SA(b, h) + aoff + m * 2048 + k * 1024); } while (0)
; #define PG8_LDB(dst, b, h) do { _Pragma("unroll") for (int n = 0; n < 2; ++n) _Pragma("unroll") for (int k = 0; k < 2; ++k) dst[n][k] = *(const PG8_LAS bf16x8*)(lds + PG8_SB(b, h) + boff + n * 2048 + k * 1024); } while (0)
; #define PG8_MMA(ai, bj, At, Bt) do { __builtin_amdgcn_s_setprio(1); _Pragma("unroll") for (int m = 0; m < 4; ++m) _Pragma("unroll") for (int n = 0; n < 2; ++n) _Pragma("unroll") for (int k = 0; k < 2; ++k) \
;         acc[ai][bj][m][n] = __builtin_amdgcn_mfma_f32_16x16x32_bf16(Bt[n][k], At[m][k], acc[ai][bj][m][n], 0, 0, 0); __builtin_amdgcn_s_setprio(0); } while (0)
; #define PG8_WAIT_V(n) asm volatile("s_waitcnt vmcnt(" #n ")" ::: "memory")
; #define PG8_WAIT_L(n) asm volatile("s_waitcnt lgkmcnt(" #n ")" ::: "memory")
; #define PG8_BAR __builtin_amdgcn_s_barrier()
; #define PG8_SCHED __builtin_amdgcn_sched_barrier(0)
; template <class Epi, class Sched, bool ALIGN_EPI = false, bool SP2 = false, bool GEN = false>
; __device__ __forceinline__ void gemm_phase(PG8_LAS unsigned char* lds, const Gemm g, const Sched& S, const Epi& E, int wave_) {
;     ...
;             PG8_LDB(B0, 1, 0); PG8_LDB(B1, 1, 1); PG8_SCHED; PG8_LDA(At, 1, 0); PG8_STAGE(PG8_SA(0, 1), a2 + hstepA, voffA);
;             PG8_WAIT_V(8); PG8_WAIT_L(0); PG8_BAR; PG8_MMA(0, 0, At, B0); PG8_MMA(0, 1, At, B1); PG8_BAR; PG8_SCHED;
;             PG8_LDA(At, 1, 1); PG8_STAGE(PG8_SB(1, 0), b3, voffB); PG8_STAGE(PG8_SB(1, 1), b3 + hstepB, voffB); PG8_STAGE(PG8_SA(1, 0), a3, voffA);
;             PG8_WAIT_V(8); PG8_WAIT_L(0); PG8_BAR; PG8_MMA(1, 0, At, B0); PG8_MMA(1, 1, At, B1); PG8_BAR; PG8_SCHED;
	s_add_i32 s24, 0, 0x18000
	s_add_i32 s39, 0, 0x1c000
	v_add_u32_e32 v158, s24, v147
	v_add_u32_e32 v174, s39, v147
	ds_read_b128 v[140:143], v158
	ds_read_b128 v[150:153], v158 offset:1024
	ds_read_b128 v[154:157], v158 offset:2048
	ds_read_b128 v[158:161], v158 offset:3072
	ds_read_b128 v[162:165], v174
	ds_read_b128 v[166:169], v174 offset:1024
	ds_read_b128 v[170:173], v174 offset:2048
	ds_read_b128 v[174:177], v174 offset:3072
	s_add_u32 s28, s28, 0x100000
	s_addc_u32 s29, s29, 0
	s_mov_b32 m0, s36
	ds_read_b128 v[178:181], v149 offset:32768
	ds_read_b128 v[182:185], v149 offset:33792
	ds_read_b128 v[186:189], v149 offset:34816
	ds_read_b128 v[190:193], v149 offset:35840
	ds_read_b128 v[194:197], v149 offset:36864
	ds_read_b128 v[198:201], v149 offset:37888
	ds_read_b128 v[202:205], v149 offset:38912
	ds_read_b128 v[206:209], v149 offset:39936
	global_load_lds_dwordx4 v134, s[28:29]
	s_mov_b32 m0, s37
	s_nop 0
	global_load_lds_dwordx4 v132, s[28:29]
	s_waitcnt vmcnt(8)
	s_waitcnt lgkmcnt(0)
	s_barrier
	s_setprio 1
	s_waitcnt lgkmcnt(0)
	v_mfma_f32_16x16x32_bf16 v[126:129], v[140:143], v[178:181], v[126:129]
	v_mfma_f32_16x16x32_bf16 v[122:125], v[154:157], v[178:181], v[122:125]
	v_mfma_f32_16x16x32_bf16 v[110:113], v[140:143], v[186:189], v[110:113]
	v_mfma_f32_16x16x32_bf16 v[106:109], v[154:157], v[186:189], v[106:109]
	v_mfma_f32_16x16x32_bf16 v[94:97], v[140:143], v[194:197], v[94:97]
	v_mfma_f32_16x16x32_bf16 v[90:93], v[154:157], v[194:197], v[90:93]
	v_mfma_f32_16x16x32_bf16 v[78:81], v[140:143], v[202:205], v[78:81]
	v_mfma_f32_16x16x32_bf16 v[74:77], v[154:157], v[202:205], v[74:77]
	v_mfma_f32_16x16x32_bf16 v[126:129], v[150:153], v[182:185], v[126:129]
	v_mfma_f32_16x16x32_bf16 v[122:125], v[158:161], v[182:185], v[122:125]
	v_mfma_f32_16x16x32_bf16 v[110:113], v[150:153], v[190:193], v[110:113]
	v_mfma_f32_16x16x32_bf16 v[106:109], v[158:161], v[190:193], v[106:109]
	v_mfma_f32_16x16x32_bf16 v[94:97], v[150:153], v[198:201], v[94:97]
	v_mfma_f32_16x16x32_bf16 v[90:93], v[158:161], v[198:201], v[90:93]
	v_mfma_f32_16x16x32_bf16 v[78:81], v[150:153], v[206:209], v[78:81]
	v_mfma_f32_16x16x32_bf16 v[74:77], v[158:161], v[206:209], v[74:77]
	s_setprio 0
	s_setprio 1
	v_mfma_f32_16x16x32_bf16 v[118:121], v[162:165], v[178:181], v[118:121]
	v_mfma_f32_16x16x32_bf16 v[114:117], v[170:173], v[178:181], v[114:117]
	v_mfma_f32_16x16x32_bf16 v[102:105], v[162:165], v[186:189], v[102:105]
	v_mfma_f32_16x16x32_bf16 v[98:101], v[170:173], v[186:189], v[98:101]
	v_mfma_f32_16x16x32_bf16 v[86:89], v[162:165], v[194:197], v[86:89]
	v_mfma_f32_16x16x32_bf16 v[82:85], v[170:173], v[194:197], v[82:85]
	v_mfma_f32_16x16x32_bf16 v[70:73], v[162:165], v[202:205], v[70:73]
	v_mfma_f32_16x16x32_bf16 v[66:69], v[170:173], v[202:205], v[66:69]
	v_mfma_f32_16x16x32_bf16 v[118:121], v[166:169], v[182:185], v[118:121]
	v_mfma_f32_16x16x32_bf16 v[114:117], v[174:177], v[182:185], v[114:117]
	v_mfma_f32_16x16x32_bf16 v[102:105], v[166:169], v[190:193], v[102:105]
	v_mfma_f32_16x16x32_bf16 v[98:101], v[174:177], v[190:193], v[98:101]
	v_mfma_f32_16x16x32_bf16 v[86:89], v[166:169], v[198:201], v[86:89]
	v_mfma_f32_16x16x32_bf16 v[82:85], v[174:177], v[198:201], v[82:85]
	v_mfma_f32_16x16x32_bf16 v[70:73], v[166:169], v[206:209], v[70:73]
	v_mfma_f32_16x16x32_bf16 v[66:69], v[174:177], v[206:209], v[66:69]
	s_setprio 0
	s_barrier
	s_add_i32 s24, s24, s18
	v_lshl_add_u64 v[144:145], v[144:145], 0, s[76:77]
	s_mov_b32 m0, s24
	ds_read_b128 v[178:181], v149 offset:49152
	ds_read_b128 v[182:185], v149 offset:50176
	ds_read_b128 v[186:189], v149 offset:51200
	ds_read_b128 v[190:193], v149 offset:52224
	ds_read_b128 v[194:197], v149 offset:53248
	ds_read_b128 v[198:201], v149 offset:54272
	ds_read_b128 v[202:205], v149 offset:55296
	ds_read_b128 v[206:209], v149 offset:56320
	global_load_lds_dwordx4 v[144:145], off
	s_add_i32 m0, s24, 0x2000
	s_add_u32 s14, s14, 0x100080
	v_lshl_add_u64 v[144:145], v[210:211], 0, s[76:77]
	s_addc_u32 s15, s15, 0
	s_add_i32 s24, s39, s18
	global_load_lds_dwordx4 v[144:145], off
	s_mov_b32 m0, s24
	s_nop 0
	global_load_lds_dwordx4 v0, s[14:15]
	s_add_i32 m0, s24, 0x2000
	s_nop 0
	global_load_lds_dwordx4 v130, s[14:15]
	v_lshl_add_u64 v[144:145], v[212:213], 0, s[76:77]
	s_mov_b32 m0, s64
	s_nop 0
	global_load_lds_dwordx4 v[144:145], off
	v_lshl_add_u64 v[144:145], v[214:215], 0, s[76:77]
	s_mov_b32 m0, s65
	s_nop 0
	global_load_lds_dwordx4 v[144:145], off
	s_waitcnt vmcnt(8)
	s_waitcnt lgkmcnt(0)
	s_barrier
	s_setprio 1
	s_waitcnt lgkmcnt(0)
	v_mfma_f32_16x16x32_bf16 v[62:65], v[140:143], v[178:181], v[62:65]
	v_mfma_f32_16x16x32_bf16 v[58:61], v[154:157], v[178:181], v[58:61]
	v_mfma_f32_16x16x32_bf16 v[46:49], v[140:143], v[186:189], v[46:49]
	v_mfma_f32_16x16x32_bf16 v[42:45], v[154:157], v[186:189], v[42:45]
	v_mfma_f32_16x16x32_bf16 v[30:33], v[140:143], v[194:197], v[30:33]
	v_mfma_f32_16x16x32_bf16 v[26:29], v[154:157], v[194:197], v[26:29]
	v_mfma_f32_16x16x32_bf16 v[14:17], v[140:143], v[202:205], v[14:17]
	v_mfma_f32_16x16x32_bf16 v[10:13], v[154:157], v[202:205], v[10:13]
	v_mfma_f32_16x16x32_bf16 v[62:65], v[150:153], v[182:185], v[62:65]
	v_mfma_f32_16x16x32_bf16 v[58:61], v[158:161], v[182:185], v[58:61]
	v_mfma_f32_16x16x32_bf16 v[46:49], v[150:153], v[190:193], v[46:49]
	v_mfma_f32_16x16x32_bf16 v[42:45], v[158:161], v[190:193], v[42:45]
	v_mfma_f32_16x16x32_bf16 v[30:33], v[150:153], v[198:201], v[30:33]
	v_mfma_f32_16x16x32_bf16 v[26:29], v[158:161], v[198:201], v[26:29]
	v_mfma_f32_16x16x32_bf16 v[14:17], v[150:153], v[206:209], v[14:17]
	v_mfma_f32_16x16x32_bf16 v[10:13], v[158:161], v[206:209], v[10:13]
	s_setprio 0
	s_setprio 1
	v_mfma_f32_16x16x32_bf16 v[54:57], v[162:165], v[178:181], v[54:57]
	v_mfma_f32_16x16x32_bf16 v[50:53], v[170:173], v[178:181], v[50:53]
	v_mfma_f32_16x16x32_bf16 v[38:41], v[162:165], v[186:189], v[38:41]
	v_mfma_f32_16x16x32_bf16 v[34:37], v[170:173], v[186:189], v[34:37]
	v_mfma_f32_16x16x32_bf16 v[22:25], v[162:165], v[194:197], v[22:25]
	v_mfma_f32_16x16x32_bf16 v[18:21], v[170:173], v[194:197], v[18:21]
	v_mfma_f32_16x16x32_bf16 v[6:9], v[162:165], v[202:205], v[6:9]
	v_mfma_f32_16x16x32_bf16 v[2:5], v[170:173], v[202:205], v[2:5]
	v_mfma_f32_16x16x32_bf16 v[54:57], v[166:169], v[182:185], v[54:57]
	v_mfma_f32_16x16x32_bf16 v[50:53], v[174:177], v[182:185], v[50:53]
	v_mfma_f32_16x16x32_bf16 v[38:41], v[166:169], v[190:193], v[38:41]
	v_mfma_f32_16x16x32_bf16 v[34:37], v[174:177], v[190:193], v[34:37]
	v_mfma_f32_16x16x32_bf16 v[22:25], v[166:169], v[198:201], v[22:25]
	v_mfma_f32_16x16x32_bf16 v[18:21], v[174:177], v[198:201], v[18:21]
	v_mfma_f32_16x16x32_bf16 v[6:9], v[166:169], v[206:209], v[6:9]
	v_mfma_f32_16x16x32_bf16 v[2:5], v[174:177], v[206:209], v[2:5]
	s_setprio 0
	s_barrier
	s_cmp_gt_i32 s38, 59
	s_cbranch_scc0 .LBB0_945
	s_and_b64 vcc, exec, s[52:53]
	s_cbranch_vccz .LBB0_948
	s_barrier

; #define PG8_STAGE(bufoff, gbase, voff) do { _Pragma("unroll") for (int _i = 0; _i < 2; ++_i) \
;         __builtin_amdgcn_global_load_lds((const unsigned*)((const char*)(gbase) + (voff)[_i]), (PG8_LAS unsigned*)(lds + (bufoff) + ldsw + _i * 8192), 16, 0, 0); } while (0)
; #define PG8_LDA(dst, b, h) do { _Pragma("unroll") for (int m = 0; m < 4; ++m) _Pragma("unroll") for (int k = 0; k < 2; ++k) dst[m][k] = *(const PG8_LAS bf16x8*)(lds + PG8_SA(b, h) + aoff + m * 2048 + k * 1024); } while (0)
; #define PG8_LDB(dst, b, h) do { _Pragma("unroll") for (int n = 0; n < 2; ++n) _Pragma("unroll") for (int k = 0; k < 2; ++k) dst[n][k] = *(const PG8_LAS bf16x8*)(lds + PG8_SB(b, h) + boff + n * 2048 + k * 1024); } while (0)
; #define PG8_SCHED __builtin_amdgcn_sched_barrier(0)
; template <class Epi, class Sched, bool ALIGN_EPI = false, bool SP2 = false, bool GEN = false>
; __device__ __forceinline__ void gemm_phase(PG8_LAS unsigned char* lds, const Gemm g, const Sched& S, const Epi& E, int wave_) {
;     ...
;         const bool has_next = S.next(ui + 1, nxt);
;         const char* nA = has_next ? (const char*)g.A + (size_t)nxt.pm * tstepA + (GEN ? S.acol(nxt) * 2 : 0) : cA; const char* nB = has_next ? (const char*)g.Bt + (size_t)nxt.pn * tstepB : cB;
;         for (int t = 0; t < nt; t += 2) {
;             const bool last = (t == nt - 2);
;             const char* a1 = cA + (size_t)(t + 1) * kstep;
;             const char* a2 = last ? nA : cA + (size_t)(t + 2) * kstep; const char* b2 = last ? nB : cB + (size_t)(t + 2) * kstep;
;             const char* a3 = a2 + kstep; const char* b3 = b2 + kstep;
;             if (last && has_next) S.a_ready(nxt);
;             if constexpr (SP2) {
;             PG8_LDB(B0, 0, 0); PG8_LDB(B1, 0, 1); PG8_SCHED; PG8_LDA(At, 0, 0); PG8_STAGE(PG8_SA(1, 1), a1 + hstepA, voffA);
;     ...
;         for (int a = 0; a < 2; ++a)
; #pragma unroll
;             for (int b = 0; b < 2; ++b)
; #pragma unroll
;                 for (int m = 0; m < 4; ++m)
; #pragma unroll
;                     for (int n = 0; n < 2; ++n) acc[a][b][m][n] = (f32x4){0.f, 0.f, 0.f, 0.f};
;         cur = nxt; cA = nA; cB = nB; ++ui;
.LBB0_1088:
	s_ashr_i32 s55, s54, 31
	s_lshl_b64 s[14:15], s[54:55], 21
	s_add_u32 s56, s34, s14
	s_addc_u32 s57, s35, s15
	s_and_b64 s[14:15], s[42:43], exec
	s_cselect_b32 s55, s57, s39
	s_cselect_b32 s67, s56, s38
	s_ashr_i32 s53, s52, 31
	s_lshl_b64 s[14:15], s[52:53], 21
	s_add_u32 s58, s44, s14
	s_addc_u32 s59, s45, s15
	s_and_b64 s[14:15], s[42:43], exec
	s_cselect_b32 s53, s59, s29
	s_cselect_b32 s72, s58, s28
	s_add_u32 s73, s28, 0x100
	s_addc_u32 s74, s29, 0
	s_add_u32 s60, s38, 0x100080
	v_mov_b32_e32 v2, 0
	s_addc_u32 s61, s39, 0
	s_mov_b32 s38, -2
	v_mov_b32_e32 v3, v2
	v_mov_b32_e32 v4, v2
	v_mov_b32_e32 v5, v2
	v_mov_b32_e32 v6, v2
	v_mov_b32_e32 v7, v2
	v_mov_b32_e32 v8, v2
	v_mov_b32_e32 v9, v2
	v_mov_b32_e32 v18, v2
	v_mov_b32_e32 v19, v2
	v_mov_b32_e32 v20, v2
	v_mov_b32_e32 v21, v2
	v_mov_b32_e32 v22, v2
	v_mov_b32_e32 v23, v2
	v_mov_b32_e32 v24, v2
	v_mov_b32_e32 v25, v2
	v_mov_b32_e32 v34, v2
	v_mov_b32_e32 v35, v2
	v_mov_b32_e32 v36, v2
	v_mov_b32_e32 v37, v2
	v_mov_b32_e32 v38, v2
	v_mov_b32_e32 v39, v2
	v_mov_b32_e32 v40, v2
	v_mov_b32_e32 v41, v2
	v_mov_b32_e32 v50, v2
	v_mov_b32_e32 v51, v2
	v_mov_b32_e32 v52, v2
	v_mov_b32_e32 v53, v2
	v_mov_b32_e32 v54, v2
	v_mov_b32_e32 v55, v2
	v_mov_b32_e32 v56, v2
	v_mov_b32_e32 v57, v2
	v_mov_b32_e32 v10, v2
	v_mov_b32_e32 v11, v2
	v_mov_b32_e32 v12, v2
	v_mov_b32_e32 v13, v2
	v_mov_b32_e32 v14, v2
	v_mov_b32_e32 v15, v2
	v_mov_b32_e32 v16, v2
	v_mov_b32_e32 v17, v2
	v_mov_b32_e32 v26, v2
	v_mov_b32_e32 v27, v2
	v_mov_b32_e32 v28, v2
	v_mov_b32_e32 v29, v2
	v_mov_b32_e32 v30, v2
	v_mov_b32_e32 v31, v2
	v_mov_b32_e32 v32, v2
	v_mov_b32_e32 v33, v2
	v_mov_b32_e32 v42, v2
	v_mov_b32_e32 v43, v2
	v_mov_b32_e32 v44, v2
	v_mov_b32_e32 v45, v2
	v_mov_b32_e32 v46, v2
	v_mov_b32_e32 v47, v2
	v_mov_b32_e32 v48, v2
	v_mov_b32_e32 v49, v2
	v_mov_b32_e32 v58, v2
	v_mov_b32_e32 v59, v2
	v_mov_b32_e32 v60, v2
	v_mov_b32_e32 v61, v2
	v_mov_b32_e32 v62, v2
	v_mov_b32_e32 v63, v2
	v_mov_b32_e32 v64, v2
	v_mov_b32_e32 v65, v2
	v_mov_b32_e32 v66, v2
	v_mov_b32_e32 v67, v2
	v_mov_b32_e32 v68, v2
	v_mov_b32_e32 v69, v2
	v_mov_b32_e32 v70, v2
	v_mov_b32_e32 v71, v2
	v_mov_b32_e32 v72, v2
	v_mov_b32_e32 v73, v2
	v_mov_b32_e32 v82, v2
	v_mov_b32_e32 v83, v2
	v_mov_b32_e32 v84, v2
	v_mov_b32_e32 v85, v2
	v_mov_b32_e32 v86, v2
	v_mov_b32_e32 v87, v2
	v_mov_b32_e32 v88, v2
	v_mov_b32_e32 v89, v2
	v_mov_b32_e32 v98, v2
	v_mov_b32_e32 v99, v2
	v_mov_b32_e32 v100, v2
	v_mov_b32_e32 v101, v2
	v_mov_b32_e32 v102, v2
	v_mov_b32_e32 v103, v2
	v_mov_b32_e32 v104, v2
	v_mov_b32_e32 v105, v2
	v_mov_b32_e32 v114, v2
	v_mov_b32_e32 v115, v2
	v_mov_b32_e32 v116, v2
	v_mov_b32_e32 v117, v2
	v_mov_b32_e32 v118, v2
	v_mov_b32_e32 v119, v2
	v_mov_b32_e32 v120, v2
	v_mov_b32_e32 v121, v2
	v_mov_b32_e32 v74, v2
	v_mov_b32_e32 v75, v2
	v_mov_b32_e32 v76, v2
	v_mov_b32_e32 v77, v2
	v_mov_b32_e32 v78, v2
	v_mov_b32_e32 v79, v2
	v_mov_b32_e32 v80, v2
	v_mov_b32_e32 v81, v2
	v_mov_b32_e32 v90, v2
	v_mov_b32_e32 v91, v2
	v_mov_b32_e32 v92, v2
	v_mov_b32_e32 v93, v2
	v_mov_b32_e32 v94, v2
	v_mov_b32_e32 v95, v2
	v_mov_b32_e32 v96, v2
	v_mov_b32_e32 v97, v2
	v_mov_b32_e32 v106, v2
	v_mov_b32_e32 v107, v2
	v_mov_b32_e32 v108, v2
	v_mov_b32_e32 v109, v2
	v_mov_b32_e32 v110, v2
	v_mov_b32_e32 v111, v2
	v_mov_b32_e32 v112, v2
	v_mov_b32_e32 v113, v2
	v_mov_b32_e32 v122, v2
	v_mov_b32_e32 v123, v2
	v_mov_b32_e32 v124, v2
	v_mov_b32_e32 v125, v2
	v_mov_b32_e32 v126, v2
	v_mov_b32_e32 v127, v2
	v_mov_b32_e32 v128, v2
	v_mov_b32_e32 v129, v2
	s_add_i32 s38, s38, -2
	s_sub_u32 s73, s73, 0x100
	s_subb_u32 s74, s74, 0
	s_sub_u32 s60, s60, 0x100
	s_subb_u32 s61, s61, 0
.LBB0_1089:
	v_add_u32_e32 v140, 0x10000, v143
	ds_read_b128 v[146:149], v140
	ds_read_b128 v[150:153], v140 offset:1024
	ds_read_b128 v[154:157], v140 offset:2048
	ds_read_b128 v[158:161], v140 offset:3072
	v_add_u32_e32 v140, 0x14000, v143
	ds_read_b128 v[162:165], v140
	ds_read_b128 v[166:169], v140 offset:1024
	ds_read_b128 v[170:173], v140 offset:2048
	ds_read_b128 v[174:177], v140 offset:3072
	s_add_i32 m0, s19, 0xc000
	ds_read_b128 v[178:181], v145
	ds_read_b128 v[182:185], v145 offset:1024
	ds_read_b128 v[186:189], v145 offset:2048
	ds_read_b128 v[190:193], v145 offset:3072
	ds_read_b128 v[194:197], v145 offset:4096
	ds_read_b128 v[198:201], v145 offset:5120
	ds_read_b128 v[202:205], v145 offset:6144
	ds_read_b128 v[206:209], v145 offset:7168
	s_add_i32 s38, s38, 2
	s_add_u32 s73, s73, 0x100
	s_addc_u32 s74, s74, 0
	s_add_u32 s60, s60, 0x100
	s_addc_u32 s61, s61, 0
	global_load_lds_dwordx4 v138, s[60:61]
	s_add_i32 m0, s19, 0xe000
	s_nop 0
	global_load_lds_dwordx4 v136, s[60:61]
	s_add_i32 s24, 0, 0x10000
	s_add_i32 s39, 0, 0x14000
	s_add_u32 s14, s60, 0xfff00080
	s_addc_u32 s15, s61, -1
	s_cmp_eq_u32 s38, 60
	s_cselect_b32 s29, s55, s15
	s_cselect_b32 s28, s67, s14
	s_cselect_b32 s15, s53, s74
	s_cselect_b32 s14, s72, s73
	s_waitcnt vmcnt(8)
	s_waitcnt lgkmcnt(0)
	s_barrier
; #define PG8_STAGE(bufoff, gbase, voff) do { _Pragma("unroll") for (int _i = 0; _i < 2; ++_i) \
;         __builtin_amdgcn_global_load_lds((const unsigned*)((const char*)(gbase) + (voff)[_i]), (PG8_LAS unsigned*)(lds + (bufoff) + ldsw + _i * 8192), 16, 0, 0); } while (0)
; #define PG8_LDA(dst, b, h) do { _Pragma("unroll") for (int m = 0; m < 4; ++m) _Pragma("unroll") for (int k = 0; k < 2; ++k) dst[m][k] = *(const PG8_LAS bf16x8*)(lds + PG8_SA(b, h) + aoff + m * 2048 + k * 1024); } while (0)
; #define PG8_MMA(ai, bj, At, Bt) do { __builtin_amdgcn_s_setprio(1); _Pragma("unroll") for (int m = 0; m < 4; ++m) _Pragma("unroll") for (int n = 0; n < 2; ++n) _Pragma("unroll") for (int k = 0; k < 2; ++k) \
;         acc[ai][bj][m][n] = __builtin_amdgcn_mfma_f32_16x16x32_bf16(Bt[n][k], At[m][k], acc[ai][bj][m][n], 0, 0, 0); __builtin_amdgcn_s_setprio(0); } while (0)
; #define PG8_WAIT_V(n) asm volatile("s_waitcnt vmcnt(" #n ")" ::: "memory")
; #define PG8_WAIT_L(n) asm volatile("s_waitcnt lgkmcnt(" #n ")" ::: "memory")
; #define PG8_BAR __builtin_amdgcn_s_barrier()
; #define PG8_SCHED __builtin_amdgcn_sched_barrier(0)
; template <class Epi, class Sched, bool ALIGN_EPI = false, bool SP2 = false, bool GEN = false>
; __device__ __forceinline__ void gemm_phase(PG8_LAS unsigned char* lds, const Gemm g, const Sched& S, const Epi& E, int wave_) {
;     ...
;             PG8_WAIT_V(8); PG8_WAIT_L(0); PG8_BAR; PG8_MMA(0, 0, At, B0); PG8_MMA(0, 1, At, B1); PG8_BAR; PG8_SCHED;
;             PG8_LDA(At, 0, 1); PG8_STAGE(PG8_SB(0, 0), b2, voffB); PG8_STAGE(PG8_SB(0, 1), b2 + hstepB, voffB); PG8_STAGE(PG8_SA(0, 0), a2, voffA);
;             PG8_WAIT_V(8); PG8_WAIT_L(0); PG8_BAR; PG8_MMA(1, 0, At, B0); PG8_MMA(1, 1, At, B1); PG8_BAR; PG8_SCHED;
	s_setprio 1
	s_waitcnt lgkmcnt(0)
	v_mfma_f32_16x16x32_bf16 v[126:129], v[146:149], v[178:181], v[126:129]
	v_mfma_f32_16x16x32_bf16 v[122:125], v[154:157], v[178:181], v[122:125]
	v_mfma_f32_16x16x32_bf16 v[110:113], v[146:149], v[186:189], v[110:113]
	v_mfma_f32_16x16x32_bf16 v[106:109], v[154:157], v[186:189], v[106:109]
	v_mfma_f32_16x16x32_bf16 v[94:97], v[146:149], v[194:197], v[94:97]
	v_mfma_f32_16x16x32_bf16 v[90:93], v[154:157], v[194:197], v[90:93]
	v_mfma_f32_16x16x32_bf16 v[78:81], v[146:149], v[202:205], v[78:81]
	v_mfma_f32_16x16x32_bf16 v[74:77], v[154:157], v[202:205], v[74:77]
	v_mfma_f32_16x16x32_bf16 v[126:129], v[150:153], v[182:185], v[126:129]
	v_mfma_f32_16x16x32_bf16 v[122:125], v[158:161], v[182:185], v[122:125]
	v_mfma_f32_16x16x32_bf16 v[110:113], v[150:153], v[190:193], v[110:113]
	v_mfma_f32_16x16x32_bf16 v[106:109], v[158:161], v[190:193], v[106:109]
	v_mfma_f32_16x16x32_bf16 v[94:97], v[150:153], v[198:201], v[94:97]
	v_mfma_f32_16x16x32_bf16 v[90:93], v[158:161], v[198:201], v[90:93]
	v_mfma_f32_16x16x32_bf16 v[78:81], v[150:153], v[206:209], v[78:81]
	v_mfma_f32_16x16x32_bf16 v[74:77], v[158:161], v[206:209], v[74:77]
	s_setprio 0
	s_setprio 1
	v_mfma_f32_16x16x32_bf16 v[118:121], v[162:165], v[178:181], v[118:121]
	v_mfma_f32_16x16x32_bf16 v[114:117], v[170:173], v[178:181], v[114:117]
	v_mfma_f32_16x16x32_bf16 v[102:105], v[162:165], v[186:189], v[102:105]
	v_mfma_f32_16x16x32_bf16 v[98:101], v[170:173], v[186:189], v[98:101]
	v_mfma_f32_16x16x32_bf16 v[86:89], v[162:165], v[194:197], v[86:89]
	v_mfma_f32_16x16x32_bf16 v[82:85], v[170:173], v[194:197], v[82:85]
	v_mfma_f32_16x16x32_bf16 v[70:73], v[162:165], v[202:205], v[70:73]
	v_mfma_f32_16x16x32_bf16 v[66:69], v[170:173], v[202:205], v[66:69]
	v_mfma_f32_16x16x32_bf16 v[118:121], v[166:169], v[182:185], v[118:121]
	v_mfma_f32_16x16x32_bf16 v[114:117], v[174:177], v[182:185], v[114:117]
	v_mfma_f32_16x16x32_bf16 v[102:105], v[166:169], v[190:193], v[102:105]
	v_mfma_f32_16x16x32_bf16 v[98:101], v[174:177], v[190:193], v[98:101]
	v_mfma_f32_16x16x32_bf16 v[86:89], v[166:169], v[198:201], v[86:89]
	v_mfma_f32_16x16x32_bf16 v[82:85], v[174:177], v[198:201], v[82:85]
	v_mfma_f32_16x16x32_bf16 v[70:73], v[166:169], v[206:209], v[70:73]
	v_mfma_f32_16x16x32_bf16 v[66:69], v[174:177], v[206:209], v[66:69]
	s_setprio 0
	s_barrier
	s_add_i32 s24, s24, s18
	v_lshl_add_u64 v[140:141], s[14:15], 0, v[0:1]
	s_mov_b32 m0, s24
	ds_read_b128 v[178:181], v145 offset:16384
	ds_read_b128 v[182:185], v145 offset:17408
	ds_read_b128 v[186:189], v145 offset:18432
	ds_read_b128 v[190:193], v145 offset:19456
	ds_read_b128 v[194:197], v145 offset:20480
	ds_read_b128 v[198:201], v145 offset:21504
	ds_read_b128 v[202:205], v145 offset:22528
	ds_read_b128 v[206:209], v145 offset:23552
	global_load_lds_dwordx4 v[140:141], off
	s_add_i32 m0, s24, 0x2000
	s_add_u32 s78, s14, 0x100000
	v_lshl_add_u64 v[210:211], s[14:15], 0, v[130:131]
	s_addc_u32 s79, s15, 0
	s_add_i32 s24, s39, s18
	global_load_lds_dwordx4 v[210:211], off
	s_mov_b32 m0, s24
	v_lshl_add_u64 v[214:215], s[28:29], 0, v[132:133]
	global_load_lds_dwordx4 v0, s[78:79]
	s_add_i32 m0, s24, 0x2000
	s_nop 0
	global_load_lds_dwordx4 v130, s[78:79]
	v_lshl_add_u64 v[212:213], s[28:29], 0, v[134:135]
	s_mov_b32 m0, s19
	s_nop 0
	global_load_lds_dwordx4 v[212:213], off
	s_mov_b32 m0, s31
	s_nop 0
	global_load_lds_dwordx4 v[214:215], off
	s_waitcnt vmcnt(8)
	s_waitcnt lgkmcnt(0)
	s_barrier
	s_setprio 1
	s_waitcnt lgkmcnt(0)
	v_mfma_f32_16x16x32_bf16 v[62:65], v[146:149], v[178:181], v[62:65]
	v_mfma_f32_16x16x32_bf16 v[58:61], v[154:157], v[178:181], v[58:61]
	v_mfma_f32_16x16x32_bf16 v[46:49], v[146:149], v[186:189], v[46:49]
	v_mfma_f32_16x16x32_bf16 v[42:45], v[154:157], v[186:189], v[42:45]
	v_mfma_f32_16x16x32_bf16 v[30:33], v[146:149], v[194:197], v[30:33]
	v_mfma_f32_16x16x32_bf16 v[26:29], v[154:157], v[194:197], v[26:29]
	v_mfma_f32_16x16x32_bf16 v[14:17], v[146:149], v[202:205], v[14:17]
	v_mfma_f32_16x16x32_bf16 v[10:13], v[154:157], v[202:205], v[10:13]
	v_mfma_f32_16x16x32_bf16 v[62:65], v[150:153], v[182:185], v[62:65]
	v_mfma_f32_16x16x32_bf16 v[58:61], v[158:161], v[182:185], v[58:61]
	v_mfma_f32_16x16x32_bf16 v[46:49], v[150:153], v[190:193], v[46:49]
	v_mfma_f32_16x16x32_bf16 v[42:45], v[158:161], v[190:193], v[42:45]
	v_mfma_f32_16x16x32_bf16 v[30:33], v[150:153], v[198:201], v[30:33]
	v_mfma_f32_16x16x32_bf16 v[26:29], v[158:161], v[198:201], v[26:29]
	v_mfma_f32_16x16x32_bf16 v[14:17], v[150:153], v[206:209], v[14:17]
	v_mfma_f32_16x16x32_bf16 v[10:13], v[158:161], v[206:209], v[10:13]
	s_setprio 0
	s_setprio 1
	v_mfma_f32_16x16x32_bf16 v[54:57], v[162:165], v[178:181], v[54:57]
	v_mfma_f32_16x16x32_bf16 v[50:53], v[170:173], v[178:181], v[50:53]
	v_mfma_f32_16x16x32_bf16 v[38:41], v[162:165], v[186:189], v[38:41]
	v_mfma_f32_16x16x32_bf16 v[34:37], v[170:173], v[186:189], v[34:37]
	v_mfma_f32_16x16x32_bf16 v[22:25], v[162:165], v[194:197], v[22:25]
	v_mfma_f32_16x16x32_bf16 v[18:21], v[170:173], v[194:197], v[18:21]
	v_mfma_f32_16x16x32_bf16 v[6:9], v[162:165], v[202:205], v[6:9]
	v_mfma_f32_16x16x32_bf16 v[2:5], v[170:173], v[202:205], v[2:5]
	v_mfma_f32_16x16x32_bf16 v[54:57], v[166:169], v[182:185], v[54:57]
	v_mfma_f32_16x16x32_bf16 v[50:53], v[174:177], v[182:185], v[50:53]
	v_mfma_f32_16x16x32_bf16 v[38:41], v[166:169], v[190:193], v[38:41]
	v_mfma_f32_16x16x32_bf16 v[34:37], v[174:177], v[190:193], v[34:37]
	v_mfma_f32_16x16x32_bf16 v[22:25], v[166:169], v[198:201], v[22:25]
	v_mfma_f32_16x16x32_bf16 v[18:21], v[174:177], v[198:201], v[18:21]
	v_mfma_f32_16x16x32_bf16 v[6:9], v[166:169], v[206:209], v[6:9]
	v_mfma_f32_16x16x32_bf16 v[2:5], v[174:177], v[206:209], v[2:5]
	s_setprio 0
	s_barrier
; #define PG8_STAGE(bufoff, gbase, voff) do { _Pragma("unroll") for (int _i = 0; _i < 2; ++_i) \
;         __builtin_amdgcn_global_load_lds((const unsigned*)((const char*)(gbase) + (voff)[_i]), (PG8_LAS unsigned*)(lds + (bufoff) + ldsw + _i * 8192), 16, 0, 0); } while (0)
; #define PG8_LDA(dst, b, h) do { _Pragma("unroll") for (int m = 0; m < 4; ++m) _Pragma("unroll") for (int k = 0; k < 2; ++k) dst[m][k] = *(const PG8_LAS bf16x8*)(lds + PG8_SA(b, h) + aoff + m * 2048 + k * 1024); } while (0)
; #define PG8_LDB(dst, b, h) do { _Pragma("unroll") for (int n = 0; n < 2; ++n) _Pragma("unroll") for (int k = 0; k < 2; ++k) dst[n][k] = *(const PG8_LAS bf16x8*)(lds + PG8_SB(b, h) + boff + n * 2048 + k * 1024); } while (0)
; #define PG8_MMA(ai, bj, At, Bt) do { __builtin_amdgcn_s_setprio(1); _Pragma("unroll") for (int m = 0; m < 4; ++m) _Pragma("unroll") for (int n = 0; n < 2; ++n) _Pragma("unroll") for (int k = 0; k < 2; ++k) \
;         acc[ai][bj][m][n] = __builtin_amdgcn_mfma_f32_16x16x32_bf16(Bt[n][k], At[m][k], acc[ai][bj][m][n], 0, 0, 0); __builtin_amdgcn_s_setprio(0); } while (0)
; #define PG8_WAIT_V(n) asm volatile("s_waitcnt vmcnt(" #n ")" ::: "memory")
; #define PG8_WAIT_L(n) asm volatile("s_waitcnt lgkmcnt(" #n ")" ::: "memory")
; #define PG8_BAR __builtin_amdgcn_s_barrier()
; #define PG8_SCHED __builtin_amdgcn_sched_barrier(0)
; template <class Epi, class Sched, bool ALIGN_EPI = false, bool SP2 = false, bool GEN = false>
; __device__ __forceinline__ void gemm_phase(PG8_LAS unsigned char* lds, const Gemm g, const Sched& S, const Epi& E, int wave_) {
;     ...
;             PG8_LDB(B0, 1, 0); PG8_LDB(B1, 1, 1); PG8_SCHED; PG8_LDA(At, 1, 0); PG8_STAGE(PG8_SA(0, 1), a2 + hstepA, voffA);
;             PG8_WAIT_V(8); PG8_WAIT_L(0); PG8_BAR; PG8_MMA(0, 0, At, B0); PG8_MMA(0, 1, At, B1); PG8_BAR; PG8_SCHED;
;             PG8_LDA(At, 1, 1); PG8_STAGE(PG8_SB(1, 0), b3, voffB); PG8_STAGE(PG8_SB(1, 1), b3 + hstepB, voffB); PG8_STAGE(PG8_SA(1, 0), a3, voffA);
;             PG8_WAIT_V(8); PG8_WAIT_L(0); PG8_BAR; PG8_MMA(1, 0, At, B0); PG8_MMA(1, 1, At, B1); PG8_BAR; PG8_SCHED;
	s_add_i32 s24, 0, 0x18000
	s_add_i32 s39, 0, 0x1c000
	v_add_u32_e32 v158, s24, v143
	v_add_u32_e32 v174, s39, v143
	ds_read_b128 v[146:149], v158
	ds_read_b128 v[150:153], v158 offset:1024
	ds_read_b128 v[154:157], v158 offset:2048
	ds_read_b128 v[158:161], v158 offset:3072
	ds_read_b128 v[162:165], v174
	ds_read_b128 v[166:169], v174 offset:1024
	ds_read_b128 v[170:173], v174 offset:2048
	ds_read_b128 v[174:177], v174 offset:3072
	s_add_u32 s28, s28, 0x100000
	s_addc_u32 s29, s29, 0
	s_mov_b32 m0, s36
	ds_read_b128 v[178:181], v145 offset:32768
	ds_read_b128 v[182:185], v145 offset:33792
	ds_read_b128 v[186:189], v145 offset:34816
	ds_read_b128 v[190:193], v145 offset:35840
	ds_read_b128 v[194:197], v145 offset:36864
	ds_read_b128 v[198:201], v145 offset:37888
	ds_read_b128 v[202:205], v145 offset:38912
	ds_read_b128 v[206:209], v145 offset:39936
	global_load_lds_dwordx4 v134, s[28:29]
	s_mov_b32 m0, s37
	s_nop 0
	global_load_lds_dwordx4 v132, s[28:29]
	s_waitcnt vmcnt(8)
	s_waitcnt lgkmcnt(0)
	s_barrier
	s_setprio 1
	s_waitcnt lgkmcnt(0)
	v_mfma_f32_16x16x32_bf16 v[126:129], v[146:149], v[178:181], v[126:129]
	v_mfma_f32_16x16x32_bf16 v[122:125], v[154:157], v[178:181], v[122:125]
	v_mfma_f32_16x16x32_bf16 v[110:113], v[146:149], v[186:189], v[110:113]
	v_mfma_f32_16x16x32_bf16 v[106:109], v[154:157], v[186:189], v[106:109]
	v_mfma_f32_16x16x32_bf16 v[94:97], v[146:149], v[194:197], v[94:97]
	v_mfma_f32_16x16x32_bf16 v[90:93], v[154:157], v[194:197], v[90:93]
	v_mfma_f32_16x16x32_bf16 v[78:81], v[146:149], v[202:205], v[78:81]
	v_mfma_f32_16x16x32_bf16 v[74:77], v[154:157], v[202:205], v[74:77]
	v_mfma_f32_16x16x32_bf16 v[126:129], v[150:153], v[182:185], v[126:129]
	v_mfma_f32_16x16x32_bf16 v[122:125], v[158:161], v[182:185], v[122:125]
	v_mfma_f32_16x16x32_bf16 v[110:113], v[150:153], v[190:193], v[110:113]
	v_mfma_f32_16x16x32_bf16 v[106:109], v[158:161], v[190:193], v[106:109]
	v_mfma_f32_16x16x32_bf16 v[94:97], v[150:153], v[198:201], v[94:97]
	v_mfma_f32_16x16x32_bf16 v[90:93], v[158:161], v[198:201], v[90:93]
	v_mfma_f32_16x16x32_bf16 v[78:81], v[150:153], v[206:209], v[78:81]
	v_mfma_f32_16x16x32_bf16 v[74:77], v[158:161], v[206:209], v[74:77]
	s_setprio 0
	s_setprio 1
	v_mfma_f32_16x16x32_bf16 v[118:121], v[162:165], v[178:181], v[118:121]
	v_mfma_f32_16x16x32_bf16 v[114:117], v[170:173], v[178:181], v[114:117]
	v_mfma_f32_16x16x32_bf16 v[102:105], v[162:165], v[186:189], v[102:105]
	v_mfma_f32_16x16x32_bf16 v[98:101], v[170:173], v[186:189], v[98:101]
	v_mfma_f32_16x16x32_bf16 v[86:89], v[162:165], v[194:197], v[86:89]
	v_mfma_f32_16x16x32_bf16 v[82:85], v[170:173], v[194:197], v[82:85]
	v_mfma_f32_16x16x32_bf16 v[70:73], v[162:165], v[202:205], v[70:73]
	v_mfma_f32_16x16x32_bf16 v[66:69], v[170:173], v[202:205], v[66:69]
	v_mfma_f32_16x16x32_bf16 v[118:121], v[166:169], v[182:185], v[118:121]
	v_mfma_f32_16x16x32_bf16 v[114:117], v[174:177], v[182:185], v[114:117]
	v_mfma_f32_16x16x32_bf16 v[102:105], v[166:169], v[190:193], v[102:105]
	v_mfma_f32_16x16x32_bf16 v[98:101], v[174:177], v[190:193], v[98:101]
	v_mfma_f32_16x16x32_bf16 v[86:89], v[166:169], v[198:201], v[86:89]
	v_mfma_f32_16x16x32_bf16 v[82:85], v[174:177], v[198:201], v[82:85]
	v_mfma_f32_16x16x32_bf16 v[70:73], v[166:169], v[206:209], v[70:73]
	v_mfma_f32_16x16x32_bf16 v[66:69], v[174:177], v[206:209], v[66:69]
	s_setprio 0
	s_barrier
	s_add_i32 s24, s24, s18
	v_lshl_add_u64 v[140:141], v[140:141], 0, s[76:77]
	s_mov_b32 m0, s24
	ds_read_b128 v[178:181], v145 offset:49152
	ds_read_b128 v[182:185], v145 offset:50176
	ds_read_b128 v[186:189], v145 offset:51200
	ds_read_b128 v[190:193], v145 offset:52224
	ds_read_b128 v[194:197], v145 offset:53248
	ds_read_b128 v[198:201], v145 offset:54272
	ds_read_b128 v[202:205], v145 offset:55296
	ds_read_b128 v[206:209], v145 offset:56320
	global_load_lds_dwordx4 v[140:141], off
	s_add_i32 m0, s24, 0x2000
	s_add_u32 s14, s14, 0x100080
	v_lshl_add_u64 v[140:141], v[210:211], 0, s[76:77]
	s_addc_u32 s15, s15, 0
	s_add_i32 s24, s39, s18
	global_load_lds_dwordx4 v[140:141], off
	s_mov_b32 m0, s24
	s_nop 0
	global_load_lds_dwordx4 v0, s[14:15]
	s_add_i32 m0, s24, 0x2000
	s_nop 0
	global_load_lds_dwordx4 v130, s[14:15]
	v_lshl_add_u64 v[140:141], v[212:213], 0, s[76:77]
	s_mov_b32 m0, s62
	s_nop 0
	global_load_lds_dwordx4 v[140:141], off
	v_lshl_add_u64 v[140:141], v[214:215], 0, s[76:77]
	s_mov_b32 m0, s63
	s_nop 0
	global_load_lds_dwordx4 v[140:141], off
	s_waitcnt vmcnt(8)
	s_waitcnt lgkmcnt(0)
	s_barrier
	s_setprio 1
	s_waitcnt lgkmcnt(0)
	v_mfma_f32_16x16x32_bf16 v[62:65], v[146:149], v[178:181], v[62:65]
	v_mfma_f32_16x16x32_bf16 v[58:61], v[154:157], v[178:181], v[58:61]
	v_mfma_f32_16x16x32_bf16 v[46:49], v[146:149], v[186:189], v[46:49]
	v_mfma_f32_16x16x32_bf16 v[42:45], v[154:157], v[186:189], v[42:45]
	v_mfma_f32_16x16x32_bf16 v[30:33], v[146:149], v[194:197], v[30:33]
	v_mfma_f32_16x16x32_bf16 v[26:29], v[154:157], v[194:197], v[26:29]
	v_mfma_f32_16x16x32_bf16 v[14:17], v[146:149], v[202:205], v[14:17]
	v_mfma_f32_16x16x32_bf16 v[10:13], v[154:157], v[202:205], v[10:13]
	v_mfma_f32_16x16x32_bf16 v[62:65], v[150:153], v[182:185], v[62:65]
	v_mfma_f32_16x16x32_bf16 v[58:61], v[158:161], v[182:185], v[58:61]
	v_mfma_f32_16x16x32_bf16 v[46:49], v[150:153], v[190:193], v[46:49]
	v_mfma_f32_16x16x32_bf16 v[42:45], v[158:161], v[190:193], v[42:45]
	v_mfma_f32_16x16x32_bf16 v[30:33], v[150:153], v[198:201], v[30:33]
	v_mfma_f32_16x16x32_bf16 v[26:29], v[158:161], v[198:201], v[26:29]
	v_mfma_f32_16x16x32_bf16 v[14:17], v[150:153], v[206:209], v[14:17]
	v_mfma_f32_16x16x32_bf16 v[10:13], v[158:161], v[206:209], v[10:13]
	s_setprio 0
	s_setprio 1
	v_mfma_f32_16x16x32_bf16 v[54:57], v[162:165], v[178:181], v[54:57]
	v_mfma_f32_16x16x32_bf16 v[50:53], v[170:173], v[178:181], v[50:53]
	v_mfma_f32_16x16x32_bf16 v[38:41], v[162:165], v[186:189], v[38:41]
	v_mfma_f32_16x16x32_bf16 v[34:37], v[170:173], v[186:189], v[34:37]
	v_mfma_f32_16x16x32_bf16 v[22:25], v[162:165], v[194:197], v[22:25]
	v_mfma_f32_16x16x32_bf16 v[18:21], v[170:173], v[194:197], v[18:21]
	v_mfma_f32_16x16x32_bf16 v[6:9], v[162:165], v[202:205], v[6:9]
	v_mfma_f32_16x16x32_bf16 v[2:5], v[170:173], v[202:205], v[2:5]
	v_mfma_f32_16x16x32_bf16 v[54:57], v[166:169], v[182:185], v[54:57]
	v_mfma_f32_16x16x32_bf16 v[50:53], v[174:177], v[182:185], v[50:53]
	v_mfma_f32_16x16x32_bf16 v[38:41], v[166:169], v[190:193], v[38:41]
	v_mfma_f32_16x16x32_bf16 v[34:37], v[174:177], v[190:193], v[34:37]
	v_mfma_f32_16x16x32_bf16 v[22:25], v[166:169], v[198:201], v[22:25]
	v_mfma_f32_16x16x32_bf16 v[18:21], v[174:177], v[198:201], v[18:21]
	v_mfma_f32_16x16x32_bf16 v[6:9], v[166:169], v[206:209], v[6:9]
	v_mfma_f32_16x16x32_bf16 v[2:5], v[174:177], v[206:209], v[2:5]
	s_setprio 0
	s_barrier
	s_cmp_gt_i32 s38, 59
	s_cbranch_scc0 .LBB0_1089
	s_and_b64 vcc, exec, s[50:51]
	s_cbranch_vccz .LBB0_1092
	s_barrier

; #define PG8_STAGE(bufoff, gbase, voff) do { _Pragma("unroll") for (int _i = 0; _i < 2; ++_i) \
;         __builtin_amdgcn_global_load_lds((const unsigned*)((const char*)(gbase) + (voff)[_i]), (PG8_LAS unsigned*)(lds + (bufoff) + ldsw + _i * 8192), 16, 0, 0); } while (0)
; #define PG8_LDA(dst, b, h) do { _Pragma("unroll") for (int m = 0; m < 4; ++m) _Pragma("unroll") for (int k = 0; k < 2; ++k) dst[m][k] = *(const PG8_LAS bf16x8*)(lds + PG8_SA(b, h) + aoff + m * 2048 + k * 1024); } while (0)
; #define PG8_LDB(dst, b, h) do { _Pragma("unroll") for (int n = 0; n < 2; ++n) _Pragma("unroll") for (int k = 0; k < 2; ++k) dst[n][k] = *(const PG8_LAS bf16x8*)(lds + PG8_SB(b, h) + boff + n * 2048 + k * 1024); } while (0)
; #define PG8_SCHED __builtin_amdgcn_sched_barrier(0)
; template <class Epi, class Sched, bool ALIGN_EPI = false, bool SP2 = false, bool GEN = false>
; __device__ __forceinline__ void gemm_phase(PG8_LAS unsigned char* lds, const Gemm g, const Sched& S, const Epi& E, int wave_) {
;     ...
;         const bool has_next = S.next(ui + 1, nxt);
;         const char* nA = has_next ? (const char*)g.A + (size_t)nxt.pm * tstepA + (GEN ? S.acol(nxt) * 2 : 0) : cA; const char* nB = has_next ? (const char*)g.Bt + (size_t)nxt.pn * tstepB : cB;
;         for (int t = 0; t < nt; t += 2) {
;             const bool last = (t == nt - 2);
;             const char* a1 = cA + (size_t)(t + 1) * kstep;
;             const char* a2 = last ? nA : cA + (size_t)(t + 2) * kstep; const char* b2 = last ? nB : cB + (size_t)(t + 2) * kstep;
;             const char* a3 = a2 + kstep; const char* b3 = b2 + kstep;
;             if (last && has_next) S.a_ready(nxt);
;             if constexpr (SP2) {
;             PG8_LDB(B0, 0, 0); PG8_LDB(B1, 0, 1); PG8_SCHED; PG8_LDA(At, 0, 0); PG8_STAGE(PG8_SA(1, 1), a1 + hstepA, voffA);
;     ...
;         for (int a = 0; a < 2; ++a)
; #pragma unroll
;             for (int b = 0; b < 2; ++b)
; #pragma unroll
;                 for (int m = 0; m < 4; ++m)
; #pragma unroll
;                     for (int n = 0; n < 2; ++n) acc[a][b][m][n] = (f32x4){0.f, 0.f, 0.f, 0.f};
;         cur = nxt; cA = nA; cB = nB; ++ui;
.LBB0_1165:
	s_ashr_i32 s55, s54, 31
	s_lshl_b64 s[14:15], s[54:55], 23
	s_add_u32 s56, s34, s14
	s_addc_u32 s57, s35, s15
	s_and_b64 s[14:15], s[40:41], exec
	s_cselect_b32 s55, s57, s39
	s_cselect_b32 s67, s56, s38
	s_ashr_i32 s53, s52, 31
	s_lshl_b64 s[14:15], s[52:53], 23
	s_add_u32 s58, s42, s14
	s_addc_u32 s59, s43, s15
	s_and_b64 s[14:15], s[40:41], exec
	s_cselect_b32 s53, s59, s29
	s_cselect_b32 s72, s58, s28
	s_add_u32 s73, s28, 0x100
	s_addc_u32 s74, s29, 0
	s_add_u32 s60, s38, 0x400080
	v_mov_b32_e32 v2, 0
	s_addc_u32 s61, s39, 0
	s_mov_b32 s38, -2
	v_mov_b32_e32 v3, v2
	v_mov_b32_e32 v4, v2
	v_mov_b32_e32 v5, v2
	v_mov_b32_e32 v6, v2
	v_mov_b32_e32 v7, v2
	v_mov_b32_e32 v8, v2
	v_mov_b32_e32 v9, v2
	v_mov_b32_e32 v18, v2
	v_mov_b32_e32 v19, v2
	v_mov_b32_e32 v20, v2
	v_mov_b32_e32 v21, v2
	v_mov_b32_e32 v22, v2
	v_mov_b32_e32 v23, v2
	v_mov_b32_e32 v24, v2
	v_mov_b32_e32 v25, v2
	v_mov_b32_e32 v34, v2
	v_mov_b32_e32 v35, v2
	v_mov_b32_e32 v36, v2
	v_mov_b32_e32 v37, v2
	v_mov_b32_e32 v38, v2
	v_mov_b32_e32 v39, v2
	v_mov_b32_e32 v40, v2
	v_mov_b32_e32 v41, v2
	v_mov_b32_e32 v50, v2
	v_mov_b32_e32 v51, v2
	v_mov_b32_e32 v52, v2
	v_mov_b32_e32 v53, v2
	v_mov_b32_e32 v54, v2
	v_mov_b32_e32 v55, v2
	v_mov_b32_e32 v56, v2
	v_mov_b32_e32 v57, v2
	v_mov_b32_e32 v10, v2
	v_mov_b32_e32 v11, v2
	v_mov_b32_e32 v12, v2
	v_mov_b32_e32 v13, v2
	v_mov_b32_e32 v14, v2
	v_mov_b32_e32 v15, v2
	v_mov_b32_e32 v16, v2
	v_mov_b32_e32 v17, v2
	v_mov_b32_e32 v26, v2
	v_mov_b32_e32 v27, v2
	v_mov_b32_e32 v28, v2
	v_mov_b32_e32 v29, v2
	v_mov_b32_e32 v30, v2
	v_mov_b32_e32 v31, v2
	v_mov_b32_e32 v32, v2
	v_mov_b32_e32 v33, v2
	v_mov_b32_e32 v42, v2
	v_mov_b32_e32 v43, v2
	v_mov_b32_e32 v44, v2
	v_mov_b32_e32 v45, v2
	v_mov_b32_e32 v46, v2
	v_mov_b32_e32 v47, v2
	v_mov_b32_e32 v48, v2
	v_mov_b32_e32 v49, v2
	v_mov_b32_e32 v58, v2
	v_mov_b32_e32 v59, v2
	v_mov_b32_e32 v60, v2
	v_mov_b32_e32 v61, v2
	v_mov_b32_e32 v62, v2
	v_mov_b32_e32 v63, v2
	v_mov_b32_e32 v64, v2
	v_mov_b32_e32 v65, v2
	v_mov_b32_e32 v66, v2
	v_mov_b32_e32 v67, v2
	v_mov_b32_e32 v68, v2
	v_mov_b32_e32 v69, v2
	v_mov_b32_e32 v70, v2
	v_mov_b32_e32 v71, v2
	v_mov_b32_e32 v72, v2
	v_mov_b32_e32 v73, v2
	v_mov_b32_e32 v82, v2
	v_mov_b32_e32 v83, v2
	v_mov_b32_e32 v84, v2
	v_mov_b32_e32 v85, v2
	v_mov_b32_e32 v86, v2
	v_mov_b32_e32 v87, v2
	v_mov_b32_e32 v88, v2
	v_mov_b32_e32 v89, v2
	v_mov_b32_e32 v98, v2
	v_mov_b32_e32 v99, v2
	v_mov_b32_e32 v100, v2
	v_mov_b32_e32 v101, v2
	v_mov_b32_e32 v102, v2
	v_mov_b32_e32 v103, v2
	v_mov_b32_e32 v104, v2
	v_mov_b32_e32 v105, v2
	v_mov_b32_e32 v114, v2
	v_mov_b32_e32 v115, v2
	v_mov_b32_e32 v116, v2
	v_mov_b32_e32 v117, v2
	v_mov_b32_e32 v118, v2
	v_mov_b32_e32 v119, v2
	v_mov_b32_e32 v120, v2
	v_mov_b32_e32 v121, v2
	v_mov_b32_e32 v74, v2
	v_mov_b32_e32 v75, v2
	v_mov_b32_e32 v76, v2
	v_mov_b32_e32 v77, v2
	v_mov_b32_e32 v78, v2
	v_mov_b32_e32 v79, v2
	v_mov_b32_e32 v80, v2
	v_mov_b32_e32 v81, v2
	v_mov_b32_e32 v90, v2
	v_mov_b32_e32 v91, v2
	v_mov_b32_e32 v92, v2
	v_mov_b32_e32 v93, v2
	v_mov_b32_e32 v94, v2
	v_mov_b32_e32 v95, v2
	v_mov_b32_e32 v96, v2
	v_mov_b32_e32 v97, v2
	v_mov_b32_e32 v106, v2
	v_mov_b32_e32 v107, v2
	v_mov_b32_e32 v108, v2
	v_mov_b32_e32 v109, v2
	v_mov_b32_e32 v110, v2
	v_mov_b32_e32 v111, v2
	v_mov_b32_e32 v112, v2
	v_mov_b32_e32 v113, v2
	v_mov_b32_e32 v122, v2
	v_mov_b32_e32 v123, v2
	v_mov_b32_e32 v124, v2
	v_mov_b32_e32 v125, v2
	v_mov_b32_e32 v126, v2
	v_mov_b32_e32 v127, v2
	v_mov_b32_e32 v128, v2
	v_mov_b32_e32 v129, v2
	s_add_i32 s38, s38, -2
	s_sub_u32 s73, s73, 0x100
	s_subb_u32 s74, s74, 0
	s_sub_u32 s60, s60, 0x100
	s_subb_u32 s61, s61, 0
.LBB0_1166:
	v_add_u32_e32 v144, 0x10000, v147
	ds_read_b128 v[140:143], v144
	ds_read_b128 v[150:153], v144 offset:1024
	ds_read_b128 v[154:157], v144 offset:2048
	ds_read_b128 v[158:161], v144 offset:3072
	v_add_u32_e32 v144, 0x14000, v147
	ds_read_b128 v[162:165], v144
	ds_read_b128 v[166:169], v144 offset:1024
	ds_read_b128 v[170:173], v144 offset:2048
	ds_read_b128 v[174:177], v144 offset:3072
	s_add_i32 m0, s19, 0xc000
	ds_read_b128 v[178:181], v149
	ds_read_b128 v[182:185], v149 offset:1024
	ds_read_b128 v[186:189], v149 offset:2048
	ds_read_b128 v[190:193], v149 offset:3072
	ds_read_b128 v[194:197], v149 offset:4096
	ds_read_b128 v[198:201], v149 offset:5120
	ds_read_b128 v[202:205], v149 offset:6144
	ds_read_b128 v[206:209], v149 offset:7168
	s_add_i32 s38, s38, 2
	s_add_u32 s73, s73, 0x100
	s_addc_u32 s74, s74, 0
	s_add_u32 s60, s60, 0x100
	s_addc_u32 s61, s61, 0
	global_load_lds_dwordx4 v138, s[60:61]
	s_add_i32 m0, s19, 0xe000
	s_nop 0
	global_load_lds_dwordx4 v136, s[60:61]
	s_add_i32 s24, 0, 0x10000
	s_add_i32 s39, 0, 0x14000
	s_add_u32 s14, s60, 0xffc00080
	s_addc_u32 s15, s61, -1
	s_cmpk_eq_i32 s38, 0xfc
	s_cselect_b32 s29, s55, s15
	s_cselect_b32 s28, s67, s14
	s_cselect_b32 s15, s53, s74
	s_cselect_b32 s14, s72, s73
	s_waitcnt vmcnt(8)
	s_waitcnt lgkmcnt(0)
	s_barrier
; #define PG8_STAGE(bufoff, gbase, voff) do { _Pragma("unroll") for (int _i = 0; _i < 2; ++_i) \
;         __builtin_amdgcn_global_load_lds((const unsigned*)((const char*)(gbase) + (voff)[_i]), (PG8_LAS unsigned*)(lds + (bufoff) + ldsw + _i * 8192), 16, 0, 0); } while (0)
; #define PG8_LDA(dst, b, h) do { _Pragma("unroll") for (int m = 0; m < 4; ++m) _Pragma("unroll") for (int k = 0; k < 2; ++k) dst[m][k] = *(const PG8_LAS bf16x8*)(lds + PG8_SA(b, h) + aoff + m * 2048 + k * 1024); } while (0)
; #define PG8_MMA(ai, bj, At, Bt) do { __builtin_amdgcn_s_setprio(1); _Pragma("unroll") for (int m = 0; m < 4; ++m) _Pragma("unroll") for (int n = 0; n < 2; ++n) _Pragma("unroll") for (int k = 0; k < 2; ++k) \
;         acc[ai][bj][m][n] = __builtin_amdgcn_mfma_f32_16x16x32_bf16(Bt[n][k], At[m][k], acc[ai][bj][m][n], 0, 0, 0); __builtin_amdgcn_s_setprio(0); } while (0)
; #define PG8_WAIT_V(n) asm volatile("s_waitcnt vmcnt(" #n ")" ::: "memory")
; #define PG8_WAIT_L(n) asm volatile("s_waitcnt lgkmcnt(" #n ")" ::: "memory")
; #define PG8_BAR __builtin_amdgcn_s_barrier()
; #define PG8_SCHED __builtin_amdgcn_sched_barrier(0)
; template <class Epi, class Sched, bool ALIGN_EPI = false, bool SP2 = false, bool GEN = false>
; __device__ __forceinline__ void gemm_phase(PG8_LAS unsigned char* lds, const Gemm g, const Sched& S, const Epi& E, int wave_) {
;     ...
;             PG8_WAIT_V(8); PG8_WAIT_L(0); PG8_BAR; PG8_MMA(0, 0, At, B0); PG8_MMA(0, 1, At, B1); PG8_BAR; PG8_SCHED;
;             PG8_LDA(At, 0, 1); PG8_STAGE(PG8_SB(0, 0), b2, voffB); PG8_STAGE(PG8_SB(0, 1), b2 + hstepB, voffB); PG8_STAGE(PG8_SA(0, 0), a2, voffA);
;             PG8_WAIT_V(8); PG8_WAIT_L(0); PG8_BAR; PG8_MMA(1, 0, At, B0); PG8_MMA(1, 1, At, B1); PG8_BAR; PG8_SCHED;
	s_setprio 1
	s_waitcnt lgkmcnt(0)
	v_mfma_f32_16x16x32_bf16 v[126:129], v[140:143], v[178:181], v[126:129]
	v_mfma_f32_16x16x32_bf16 v[122:125], v[154:157], v[178:181], v[122:125]
	v_mfma_f32_16x16x32_bf16 v[110:113], v[140:143], v[186:189], v[110:113]
	v_mfma_f32_16x16x32_bf16 v[106:109], v[154:157], v[186:189], v[106:109]
	v_mfma_f32_16x16x32_bf16 v[94:97], v[140:143], v[194:197], v[94:97]
	v_mfma_f32_16x16x32_bf16 v[90:93], v[154:157], v[194:197], v[90:93]
	v_mfma_f32_16x16x32_bf16 v[78:81], v[140:143], v[202:205], v[78:81]
	v_mfma_f32_16x16x32_bf16 v[74:77], v[154:157], v[202:205], v[74:77]
	v_mfma_f32_16x16x32_bf16 v[126:129], v[150:153], v[182:185], v[126:129]
	v_mfma_f32_16x16x32_bf16 v[122:125], v[158:161], v[182:185], v[122:125]
	v_mfma_f32_16x16x32_bf16 v[110:113], v[150:153], v[190:193], v[110:113]
	v_mfma_f32_16x16x32_bf16 v[106:109], v[158:161], v[190:193], v[106:109]
	v_mfma_f32_16x16x32_bf16 v[94:97], v[150:153], v[198:201], v[94:97]
	v_mfma_f32_16x16x32_bf16 v[90:93], v[158:161], v[198:201], v[90:93]
	v_mfma_f32_16x16x32_bf16 v[78:81], v[150:153], v[206:209], v[78:81]
	v_mfma_f32_16x16x32_bf16 v[74:77], v[158:161], v[206:209], v[74:77]
	s_setprio 0
	s_setprio 1
	v_mfma_f32_16x16x32_bf16 v[118:121], v[162:165], v[178:181], v[118:121]
	v_mfma_f32_16x16x32_bf16 v[114:117], v[170:173], v[178:181], v[114:117]
	v_mfma_f32_16x16x32_bf16 v[102:105], v[162:165], v[186:189], v[102:105]
	v_mfma_f32_16x16x32_bf16 v[98:101], v[170:173], v[186:189], v[98:101]
	v_mfma_f32_16x16x32_bf16 v[86:89], v[162:165], v[194:197], v[86:89]
	v_mfma_f32_16x16x32_bf16 v[82:85], v[170:173], v[194:197], v[82:85]
	v_mfma_f32_16x16x32_bf16 v[70:73], v[162:165], v[202:205], v[70:73]
	v_mfma_f32_16x16x32_bf16 v[66:69], v[170:173], v[202:205], v[66:69]
	v_mfma_f32_16x16x32_bf16 v[118:121], v[166:169], v[182:185], v[118:121]
	v_mfma_f32_16x16x32_bf16 v[114:117], v[174:177], v[182:185], v[114:117]
	v_mfma_f32_16x16x32_bf16 v[102:105], v[166:169], v[190:193], v[102:105]
	v_mfma_f32_16x16x32_bf16 v[98:101], v[174:177], v[190:193], v[98:101]
	v_mfma_f32_16x16x32_bf16 v[86:89], v[166:169], v[198:201], v[86:89]
	v_mfma_f32_16x16x32_bf16 v[82:85], v[174:177], v[198:201], v[82:85]
	v_mfma_f32_16x16x32_bf16 v[70:73], v[166:169], v[206:209], v[70:73]
	v_mfma_f32_16x16x32_bf16 v[66:69], v[174:177], v[206:209], v[66:69]
	s_setprio 0
	s_barrier
	s_add_i32 s24, s24, s18
	v_lshl_add_u64 v[144:145], s[14:15], 0, v[0:1]
	s_mov_b32 m0, s24
	ds_read_b128 v[178:181], v149 offset:16384
	ds_read_b128 v[182:185], v149 offset:17408
	ds_read_b128 v[186:189], v149 offset:18432
	ds_read_b128 v[190:193], v149 offset:19456
	ds_read_b128 v[194:197], v149 offset:20480
	ds_read_b128 v[198:201], v149 offset:21504
	ds_read_b128 v[202:205], v149 offset:22528
	ds_read_b128 v[206:209], v149 offset:23552
	global_load_lds_dwordx4 v[144:145], off
	s_add_i32 m0, s24, 0x2000
	s_add_u32 s78, s14, 0x400000
	v_lshl_add_u64 v[210:211], s[14:15], 0, v[130:131]
	s_addc_u32 s79, s15, 0
	s_add_i32 s24, s39, s18
	global_load_lds_dwordx4 v[210:211], off
	s_mov_b32 m0, s24
	v_lshl_add_u64 v[214:215], s[28:29], 0, v[132:133]
	global_load_lds_dwordx4 v0, s[78:79]
	s_add_i32 m0, s24, 0x2000
	s_nop 0
	global_load_lds_dwordx4 v130, s[78:79]
	v_lshl_add_u64 v[212:213], s[28:29], 0, v[134:135]
	s_mov_b32 m0, s19
	s_nop 0
	global_load_lds_dwordx4 v[212:213], off
	s_mov_b32 m0, s31
	s_nop 0
	global_load_lds_dwordx4 v[214:215], off
	s_waitcnt vmcnt(8)
	s_waitcnt lgkmcnt(0)
	s_barrier
	s_setprio 1
	s_waitcnt lgkmcnt(0)
	v_mfma_f32_16x16x32_bf16 v[62:65], v[140:143], v[178:181], v[62:65]
	v_mfma_f32_16x16x32_bf16 v[58:61], v[154:157], v[178:181], v[58:61]
	v_mfma_f32_16x16x32_bf16 v[46:49], v[140:143], v[186:189], v[46:49]
	v_mfma_f32_16x16x32_bf16 v[42:45], v[154:157], v[186:189], v[42:45]
	v_mfma_f32_16x16x32_bf16 v[30:33], v[140:143], v[194:197], v[30:33]
	v_mfma_f32_16x16x32_bf16 v[26:29], v[154:157], v[194:197], v[26:29]
	v_mfma_f32_16x16x32_bf16 v[14:17], v[140:143], v[202:205], v[14:17]
	v_mfma_f32_16x16x32_bf16 v[10:13], v[154:157], v[202:205], v[10:13]
	v_mfma_f32_16x16x32_bf16 v[62:65], v[150:153], v[182:185], v[62:65]
	v_mfma_f32_16x16x32_bf16 v[58:61], v[158:161], v[182:185], v[58:61]
	v_mfma_f32_16x16x32_bf16 v[46:49], v[150:153], v[190:193], v[46:49]
	v_mfma_f32_16x16x32_bf16 v[42:45], v[158:161], v[190:193], v[42:45]
	v_mfma_f32_16x16x32_bf16 v[30:33], v[150:153], v[198:201], v[30:33]
	v_mfma_f32_16x16x32_bf16 v[26:29], v[158:161], v[198:201], v[26:29]
	v_mfma_f32_16x16x32_bf16 v[14:17], v[150:153], v[206:209], v[14:17]
	v_mfma_f32_16x16x32_bf16 v[10:13], v[158:161], v[206:209], v[10:13]
	s_setprio 0
	s_setprio 1
	v_mfma_f32_16x16x32_bf16 v[54:57], v[162:165], v[178:181], v[54:57]
	v_mfma_f32_16x16x32_bf16 v[50:53], v[170:173], v[178:181], v[50:53]
	v_mfma_f32_16x16x32_bf16 v[38:41], v[162:165], v[186:189], v[38:41]
	v_mfma_f32_16x16x32_bf16 v[34:37], v[170:173], v[186:189], v[34:37]
	v_mfma_f32_16x16x32_bf16 v[22:25], v[162:165], v[194:197], v[22:25]
	v_mfma_f32_16x16x32_bf16 v[18:21], v[170:173], v[194:197], v[18:21]
	v_mfma_f32_16x16x32_bf16 v[6:9], v[162:165], v[202:205], v[6:9]
	v_mfma_f32_16x16x32_bf16 v[2:5], v[170:173], v[202:205], v[2:5]
	v_mfma_f32_16x16x32_bf16 v[54:57], v[166:169], v[182:185], v[54:57]
	v_mfma_f32_16x16x32_bf16 v[50:53], v[174:177], v[182:185], v[50:53]
	v_mfma_f32_16x16x32_bf16 v[38:41], v[166:169], v[190:193], v[38:41]
	v_mfma_f32_16x16x32_bf16 v[34:37], v[174:177], v[190:193], v[34:37]
	v_mfma_f32_16x16x32_bf16 v[22:25], v[166:169], v[198:201], v[22:25]
	v_mfma_f32_16x16x32_bf16 v[18:21], v[174:177], v[198:201], v[18:21]
	v_mfma_f32_16x16x32_bf16 v[6:9], v[166:169], v[206:209], v[6:9]
	v_mfma_f32_16x16x32_bf16 v[2:5], v[174:177], v[206:209], v[2:5]
	s_setprio 0
	s_barrier
; #define PG8_STAGE(bufoff, gbase, voff) do { _Pragma("unroll") for (int _i = 0; _i < 2; ++_i) \
;         __builtin_amdgcn_global_load_lds((const unsigned*)((const char*)(gbase) + (voff)[_i]), (PG8_LAS unsigned*)(lds + (bufoff) + ldsw + _i * 8192), 16, 0, 0); } while (0)
; #define PG8_LDA(dst, b, h) do { _Pragma("unroll") for (int m = 0; m < 4; ++m) _Pragma("unroll") for (int k = 0; k < 2; ++k) dst[m][k] = *(const PG8_LAS bf16x8*)(lds + PG8_SA(b, h) + aoff + m * 2048 + k * 1024); } while (0)
; #define PG8_LDB(dst, b, h) do { _Pragma("unroll") for (int n = 0; n < 2; ++n) _Pragma("unroll") for (int k = 0; k < 2; ++k) dst[n][k] = *(const PG8_LAS bf16x8*)(lds + PG8_SB(b, h) + boff + n * 2048 + k * 1024); } while (0)
; #define PG8_MMA(ai, bj, At, Bt) do { __builtin_amdgcn_s_setprio(1); _Pragma("unroll") for (int m = 0; m < 4; ++m) _Pragma("unroll") for (int n = 0; n < 2; ++n) _Pragma("unroll") for (int k = 0; k < 2; ++k) \
;         acc[ai][bj][m][n] = __builtin_amdgcn_mfma_f32_16x16x32_bf16(Bt[n][k], At[m][k], acc[ai][bj][m][n], 0, 0, 0); __builtin_amdgcn_s_setprio(0); } while (0)
; #define PG8_WAIT_V(n) asm volatile("s_waitcnt vmcnt(" #n ")" ::: "memory")
; #define PG8_WAIT_L(n) asm volatile("s_waitcnt lgkmcnt(" #n ")" ::: "memory")
; #define PG8_BAR __builtin_amdgcn_s_barrier()
; #define PG8_SCHED __builtin_amdgcn_sched_barrier(0)
; template <class Epi, class Sched, bool ALIGN_EPI = false, bool SP2 = false, bool GEN = false>
; __device__ __forceinline__ void gemm_phase(PG8_LAS unsigned char* lds, const Gemm g, const Sched& S, const Epi& E, int wave_) {
;     ...
;             PG8_LDB(B0, 1, 0); PG8_LDB(B1, 1, 1); PG8_SCHED; PG8_LDA(At, 1, 0); PG8_STAGE(PG8_SA(0, 1), a2 + hstepA, voffA);
;             PG8_WAIT_V(8); PG8_WAIT_L(0); PG8_BAR; PG8_MMA(0, 0, At, B0); PG8_MMA(0, 1, At, B1); PG8_BAR; PG8_SCHED;
;             PG8_LDA(At, 1, 1); PG8_STAGE(PG8_SB(1, 0), b3, voffB); PG8_STAGE(PG8_SB(1, 1), b3 + hstepB, voffB); PG8_STAGE(PG8_SA(1, 0), a3, voffA);
;             PG8_WAIT_V(8); PG8_WAIT_L(0); PG8_BAR; PG8_MMA(1, 0, At, B0); PG8_MMA(1, 1, At, B1); PG8_BAR; PG8_SCHED;
	s_add_i32 s24, 0, 0x18000
	s_add_i32 s39, 0, 0x1c000
	v_add_u32_e32 v158, s24, v147
	v_add_u32_e32 v174, s39, v147
	ds_read_b128 v[140:143], v158
	ds_read_b128 v[150:153], v158 offset:1024
	ds_read_b128 v[154:157], v158 offset:2048
	ds_read_b128 v[158:161], v158 offset:3072
	ds_read_b128 v[162:165], v174
	ds_read_b128 v[166:169], v174 offset:1024
	ds_read_b128 v[170:173], v174 offset:2048
	ds_read_b128 v[174:177], v174 offset:3072
	s_add_u32 s28, s28, 0x400000
	s_addc_u32 s29, s29, 0
	s_mov_b32 m0, s36
	ds_read_b128 v[178:181], v149 offset:32768
	ds_read_b128 v[182:185], v149 offset:33792
	ds_read_b128 v[186:189], v149 offset:34816
	ds_read_b128 v[190:193], v149 offset:35840
	ds_read_b128 v[194:197], v149 offset:36864
	ds_read_b128 v[198:201], v149 offset:37888
	ds_read_b128 v[202:205], v149 offset:38912
	ds_read_b128 v[206:209], v149 offset:39936
	global_load_lds_dwordx4 v134, s[28:29]
	s_mov_b32 m0, s37
	s_nop 0
	global_load_lds_dwordx4 v132, s[28:29]
	s_waitcnt vmcnt(8)
	s_waitcnt lgkmcnt(0)
	s_barrier
	s_setprio 1
	s_waitcnt lgkmcnt(0)
	v_mfma_f32_16x16x32_bf16 v[126:129], v[140:143], v[178:181], v[126:129]
	v_mfma_f32_16x16x32_bf16 v[122:125], v[154:157], v[178:181], v[122:125]
	v_mfma_f32_16x16x32_bf16 v[110:113], v[140:143], v[186:189], v[110:113]
	v_mfma_f32_16x16x32_bf16 v[106:109], v[154:157], v[186:189], v[106:109]
	v_mfma_f32_16x16x32_bf16 v[94:97], v[140:143], v[194:197], v[94:97]
	v_mfma_f32_16x16x32_bf16 v[90:93], v[154:157], v[194:197], v[90:93]
	v_mfma_f32_16x16x32_bf16 v[78:81], v[140:143], v[202:205], v[78:81]
	v_mfma_f32_16x16x32_bf16 v[74:77], v[154:157], v[202:205], v[74:77]
	v_mfma_f32_16x16x32_bf16 v[126:129], v[150:153], v[182:185], v[126:129]
	v_mfma_f32_16x16x32_bf16 v[122:125], v[158:161], v[182:185], v[122:125]
	v_mfma_f32_16x16x32_bf16 v[110:113], v[150:153], v[190:193], v[110:113]
	v_mfma_f32_16x16x32_bf16 v[106:109], v[158:161], v[190:193], v[106:109]
	v_mfma_f32_16x16x32_bf16 v[94:97], v[150:153], v[198:201], v[94:97]
	v_mfma_f32_16x16x32_bf16 v[90:93], v[158:161], v[198:201], v[90:93]
	v_mfma_f32_16x16x32_bf16 v[78:81], v[150:153], v[206:209], v[78:81]
	v_mfma_f32_16x16x32_bf16 v[74:77], v[158:161], v[206:209], v[74:77]
	s_setprio 0
	s_setprio 1
	v_mfma_f32_16x16x32_bf16 v[118:121], v[162:165], v[178:181], v[118:121]
	v_mfma_f32_16x16x32_bf16 v[114:117], v[170:173], v[178:181], v[114:117]
	v_mfma_f32_16x16x32_bf16 v[102:105], v[162:165], v[186:189], v[102:105]
	v_mfma_f32_16x16x32_bf16 v[98:101], v[170:173], v[186:189], v[98:101]
	v_mfma_f32_16x16x32_bf16 v[86:89], v[162:165], v[194:197], v[86:89]
	v_mfma_f32_16x16x32_bf16 v[82:85], v[170:173], v[194:197], v[82:85]
	v_mfma_f32_16x16x32_bf16 v[70:73], v[162:165], v[202:205], v[70:73]
	v_mfma_f32_16x16x32_bf16 v[66:69], v[170:173], v[202:205], v[66:69]
	v_mfma_f32_16x16x32_bf16 v[118:121], v[166:169], v[182:185], v[118:121]
	v_mfma_f32_16x16x32_bf16 v[114:117], v[174:177], v[182:185], v[114:117]
	v_mfma_f32_16x16x32_bf16 v[102:105], v[166:169], v[190:193], v[102:105]
	v_mfma_f32_16x16x32_bf16 v[98:101], v[174:177], v[190:193], v[98:101]
	v_mfma_f32_16x16x32_bf16 v[86:89], v[166:169], v[198:201], v[86:89]
	v_mfma_f32_16x16x32_bf16 v[82:85], v[174:177], v[198:201], v[82:85]
	v_mfma_f32_16x16x32_bf16 v[70:73], v[166:169], v[206:209], v[70:73]
	v_mfma_f32_16x16x32_bf16 v[66:69], v[174:177], v[206:209], v[66:69]
	s_setprio 0
	s_barrier
	s_add_i32 s24, s24, s18
	v_lshl_add_u64 v[144:145], v[144:145], 0, s[76:77]
	s_mov_b32 m0, s24
	ds_read_b128 v[178:181], v149 offset:49152
	ds_read_b128 v[182:185], v149 offset:50176
	ds_read_b128 v[186:189], v149 offset:51200
	ds_read_b128 v[190:193], v149 offset:52224
	ds_read_b128 v[194:197], v149 offset:53248
	ds_read_b128 v[198:201], v149 offset:54272
	ds_read_b128 v[202:205], v149 offset:55296
	ds_read_b128 v[206:209], v149 offset:56320
	global_load_lds_dwordx4 v[144:145], off
	s_add_i32 m0, s24, 0x2000
	s_add_u32 s14, s14, 0x400080
	v_lshl_add_u64 v[144:145], v[210:211], 0, s[76:77]
	s_addc_u32 s15, s15, 0
	s_add_i32 s24, s39, s18
	global_load_lds_dwordx4 v[144:145], off
	s_mov_b32 m0, s24
	s_nop 0
	global_load_lds_dwordx4 v0, s[14:15]
	s_add_i32 m0, s24, 0x2000
	s_nop 0
	global_load_lds_dwordx4 v130, s[14:15]
	v_lshl_add_u64 v[144:145], v[212:213], 0, s[76:77]
	s_mov_b32 m0, s62
	s_nop 0
	global_load_lds_dwordx4 v[144:145], off
	v_lshl_add_u64 v[144:145], v[214:215], 0, s[76:77]
	s_mov_b32 m0, s63
	s_nop 0
	global_load_lds_dwordx4 v[144:145], off
	s_waitcnt vmcnt(8)
	s_waitcnt lgkmcnt(0)
	s_barrier
	s_setprio 1
	s_waitcnt lgkmcnt(0)
	v_mfma_f32_16x16x32_bf16 v[62:65], v[140:143], v[178:181], v[62:65]
	v_mfma_f32_16x16x32_bf16 v[58:61], v[154:157], v[178:181], v[58:61]
	v_mfma_f32_16x16x32_bf16 v[46:49], v[140:143], v[186:189], v[46:49]
	v_mfma_f32_16x16x32_bf16 v[42:45], v[154:157], v[186:189], v[42:45]
	v_mfma_f32_16x16x32_bf16 v[30:33], v[140:143], v[194:197], v[30:33]
	v_mfma_f32_16x16x32_bf16 v[26:29], v[154:157], v[194:197], v[26:29]
	v_mfma_f32_16x16x32_bf16 v[14:17], v[140:143], v[202:205], v[14:17]
	v_mfma_f32_16x16x32_bf16 v[10:13], v[154:157], v[202:205], v[10:13]
	v_mfma_f32_16x16x32_bf16 v[62:65], v[150:153], v[182:185], v[62:65]
	v_mfma_f32_16x16x32_bf16 v[58:61], v[158:161], v[182:185], v[58:61]
	v_mfma_f32_16x16x32_bf16 v[46:49], v[150:153], v[190:193], v[46:49]
	v_mfma_f32_16x16x32_bf16 v[42:45], v[158:161], v[190:193], v[42:45]
	v_mfma_f32_16x16x32_bf16 v[30:33], v[150:153], v[198:201], v[30:33]
	v_mfma_f32_16x16x32_bf16 v[26:29], v[158:161], v[198:201], v[26:29]
	v_mfma_f32_16x16x32_bf16 v[14:17], v[150:153], v[206:209], v[14:17]
	v_mfma_f32_16x16x32_bf16 v[10:13], v[158:161], v[206:209], v[10:13]
	s_setprio 0
	s_setprio 1
	v_mfma_f32_16x16x32_bf16 v[54:57], v[162:165], v[178:181], v[54:57]
	v_mfma_f32_16x16x32_bf16 v[50:53], v[170:173], v[178:181], v[50:53]
	v_mfma_f32_16x16x32_bf16 v[38:41], v[162:165], v[186:189], v[38:41]
	v_mfma_f32_16x16x32_bf16 v[34:37], v[170:173], v[186:189], v[34:37]
	v_mfma_f32_16x16x32_bf16 v[22:25], v[162:165], v[194:197], v[22:25]
	v_mfma_f32_16x16x32_bf16 v[18:21], v[170:173], v[194:197], v[18:21]
	v_mfma_f32_16x16x32_bf16 v[6:9], v[162:165], v[202:205], v[6:9]
	v_mfma_f32_16x16x32_bf16 v[2:5], v[170:173], v[202:205], v[2:5]
	v_mfma_f32_16x16x32_bf16 v[54:57], v[166:169], v[182:185], v[54:57]
	v_mfma_f32_16x16x32_bf16 v[50:53], v[174:177], v[182:185], v[50:53]
	v_mfma_f32_16x16x32_bf16 v[38:41], v[166:169], v[190:193], v[38:41]
	v_mfma_f32_16x16x32_bf16 v[34:37], v[174:177], v[190:193], v[34:37]
	v_mfma_f32_16x16x32_bf16 v[22:25], v[166:169], v[198:201], v[22:25]
	v_mfma_f32_16x16x32_bf16 v[18:21], v[174:177], v[198:201], v[18:21]
	v_mfma_f32_16x16x32_bf16 v[6:9], v[166:169], v[206:209], v[6:9]
	v_mfma_f32_16x16x32_bf16 v[2:5], v[174:177], v[206:209], v[2:5]
	s_setprio 0
	s_barrier
	s_cmp_gt_i32 s38, 251
	s_cbranch_scc0 .LBB0_1166
	s_and_b64 vcc, exec, s[50:51]
	s_cbranch_vccz .LBB0_1169
	s_barrier
